# K-loops: dropped the already-satisfied lgkmcnt(0) behind each pre-MFMA barrier (compute segments start with their first MFMA)
# baseline (speedup 1.0000x reference)
; #define PG8_STAGE(bufoff, gbase, voff) do { _Pragma("unroll") for (int _i = 0; _i < 2; ++_i) \
;         __builtin_amdgcn_global_load_lds((const unsigned*)((const char*)(gbase) + (voff)[_i]), (PG8_LAS unsigned*)(lds + (bufoff) + ldsw + _i * 8192), 16, 0, 0); } while (0)
; #define PG8_LDA(dst, b, h) do { _Pragma("unroll") for (int m = 0; m < 4; ++m) _Pragma("unroll") for (int k = 0; k < 2; ++k) dst[m][k] = *(const PG8_LAS bf16x8*)(lds + PG8_SA(b, h) + aoff + m * 2048 + k * 1024); } while (0)
; #define PG8_LDB(dst, b, h) do { _Pragma("unroll") for (int n = 0; n < 2; ++n) _Pragma("unroll") for (int k = 0; k < 2; ++k) dst[n][k] = *(const PG8_LAS bf16x8*)(lds + PG8_SB(b, h) + boff + n * 2048 + k * 1024); } while (0)
; #define PG8_WAIT_V(n) asm volatile("s_waitcnt vmcnt(" #n ")" ::: "memory")
; #define PG8_WAIT_L(n) asm volatile("s_waitcnt lgkmcnt(" #n ")" ::: "memory")
; #define PG8_BAR __builtin_amdgcn_s_barrier()
; #define PG8_SCHED __builtin_amdgcn_sched_barrier(0)
; template <class Epi, class Sched, bool ALIGN_EPI = false, bool SP2 = false>
; __device__ __forceinline__ void gemm_phase(PG8_LAS unsigned char* lds, const Gemm g, const Sched& S, const Epi& E, const int tid) {
;     ...
;         const bool has_next = S.next(ui + 1, nxt);
;         const char* nA = has_next ? (const char*)g.A + (size_t)nxt.pm * tstep : cA; const char* nB = has_next ? (const char*)g.Bt + (size_t)nxt.pn * tstep : cB;
;         for (int t = 0; t < nt; t += 2) {
;             const bool last = (t == nt - 2);
;             const char* a1 = cA + (size_t)(t + 1) * kstep;
;             const char* a2 = last ? nA : cA + (size_t)(t + 2) * kstep; const char* b2 = last ? nB : cB + (size_t)(t + 2) * kstep;
;             const char* a3 = a2 + kstep; const char* b3 = b2 + kstep;
;             if (last && has_next) S.a_ready(nxt);
;             if constexpr (SP2) {
;             PG8_LDB(B0, 0, 0); PG8_LDB(B1, 0, 1); PG8_SCHED; PG8_LDA(At, 0, 0); PG8_STAGE(PG8_SA(1, 1), a1 + hstep, voffA);
;             PG8_WAIT_V(8); PG8_WAIT_L(0); PG8_BAR; PG8_MMA(0, 0, At, B0); PG8_MMA(0, 1, At, B1); PG8_BAR; PG8_SCHED;
;             PG8_LDA(At, 0, 1); PG8_STAGE(PG8_SB(0, 0), b2, voffB); PG8_STAGE(PG8_SB(0, 1), b2 + hstep, voffB); PG8_STAGE(PG8_SA(0, 0), a2, voffA);
;             PG8_WAIT_V(8); PG8_WAIT_L(0); PG8_BAR; PG8_MMA(1, 0, At, B0); PG8_MMA(1, 1, At, B1); PG8_BAR; PG8_SCHED;
.LBB0_149:
	s_ashr_i32 s85, s84, 31
	s_lshl_b64 s[6:7], s[84:85], 19
	s_add_u32 s56, s88, s6
	s_addc_u32 s57, s89, s7
	s_and_b64 s[6:7], s[8:9], exec
	s_cselect_b32 s1, s57, s11
	s_cselect_b32 s6, s56, s10
	s_ashr_i32 s53, s52, 31
	s_lshl_b64 s[12:13], s[52:53], 19
	s_add_u32 s58, s82, s12
	s_addc_u32 s59, s43, s13
	s_and_b64 s[12:13], s[8:9], exec
	s_cselect_b32 s7, s59, s3
	s_cselect_b32 s14, s58, s2
	s_add_u32 s15, s2, 0x100
	s_addc_u32 s16, s3, 0
	s_add_u32 s2, s10, 0x40080
	s_addc_u32 s3, s11, 0
	s_mov_b32 s17, -2
	s_add_u32 s10, s2, 0xfffc0080
	s_addc_u32 s11, s3, -1
	s_add_i32 s20, 0, 0x10000
	s_cmp_eq_u32 s17, 12
	s_cselect_b32 s13, s1, s11
	s_cselect_b32 s12, s6, s10
	s_cselect_b32 s11, s7, s16
	s_cselect_b32 s10, s14, s15
	s_add_i32 s53, 0, 0x14000
	v_add_u32_e32 v140, s20, v162
	v_add_u32_e32 v164, s53, v162
	ds_read_b128 v[128:131], v140
	ds_read_b128 v[132:135], v140 offset:1024
	ds_read_b128 v[136:139], v140 offset:2048
	ds_read_b128 v[140:143], v140 offset:3072
	ds_read_b128 v[156:159], v164
	ds_read_b128 v[180:183], v164 offset:1024
	ds_read_b128 v[184:187], v164 offset:2048
	ds_read_b128 v[188:191], v164 offset:3072
	v_lshl_add_u64 v[166:167], s[2:3], 0, v[154:155]
	s_add_i32 m0, s51, 0xc000
	ds_read_b128 v[192:195], v163
	ds_read_b128 v[196:199], v163 offset:1024
	ds_read_b128 v[214:217], v163 offset:2048
	ds_read_b128 v[218:221], v163 offset:3072
	ds_read_b128 v[222:225], v163 offset:4096
	ds_read_b128 v[226:229], v163 offset:5120
	ds_read_b128 v[230:233], v163 offset:6144
	ds_read_b128 v[234:237], v163 offset:7168
	global_load_lds_dwordx4 v[166:167], off
	v_lshl_add_u64 v[166:167], s[2:3], 0, v[152:153]
	s_add_i32 m0, s51, 0xe000
	s_nop 0
	global_load_lds_dwordx4 v[166:167], off
	s_waitcnt vmcnt(8)
	s_waitcnt lgkmcnt(0)
	s_barrier
	v_mfma_f32_16x16x32_bf16 v[120:123], v[128:131], v[192:195], 0
	v_mfma_f32_16x16x32_bf16 v[124:127], v[136:139], v[192:195], 0
	v_mfma_f32_16x16x32_bf16 v[112:115], v[128:131], v[214:217], 0
	v_mfma_f32_16x16x32_bf16 v[116:119], v[136:139], v[214:217], 0
	v_mfma_f32_16x16x32_bf16 v[104:107], v[128:131], v[222:225], 0
	v_mfma_f32_16x16x32_bf16 v[108:111], v[136:139], v[222:225], 0
	v_mfma_f32_16x16x32_bf16 v[96:99], v[128:131], v[230:233], 0
	v_mfma_f32_16x16x32_bf16 v[100:103], v[136:139], v[230:233], 0
	v_mfma_f32_16x16x32_bf16 v[120:123], v[132:135], v[196:199], v[120:123]
	v_mfma_f32_16x16x32_bf16 v[124:127], v[140:143], v[196:199], v[124:127]
	v_mfma_f32_16x16x32_bf16 v[112:115], v[132:135], v[218:221], v[112:115]
	v_mfma_f32_16x16x32_bf16 v[116:119], v[140:143], v[218:221], v[116:119]
	v_mfma_f32_16x16x32_bf16 v[104:107], v[132:135], v[226:229], v[104:107]
	v_mfma_f32_16x16x32_bf16 v[108:111], v[140:143], v[226:229], v[108:111]
	v_mfma_f32_16x16x32_bf16 v[96:99], v[132:135], v[234:237], v[96:99]
	v_mfma_f32_16x16x32_bf16 v[100:103], v[140:143], v[234:237], v[100:103]
	v_mfma_f32_16x16x32_bf16 v[56:59], v[156:159], v[192:195], 0
	v_mfma_f32_16x16x32_bf16 v[60:63], v[184:187], v[192:195], 0
	v_mfma_f32_16x16x32_bf16 v[48:51], v[156:159], v[214:217], 0
	v_mfma_f32_16x16x32_bf16 v[52:55], v[184:187], v[214:217], 0
	v_mfma_f32_16x16x32_bf16 v[40:43], v[156:159], v[222:225], 0
	v_mfma_f32_16x16x32_bf16 v[44:47], v[184:187], v[222:225], 0
	v_mfma_f32_16x16x32_bf16 v[32:35], v[156:159], v[230:233], 0
	v_mfma_f32_16x16x32_bf16 v[36:39], v[184:187], v[230:233], 0
	v_mfma_f32_16x16x32_bf16 v[56:59], v[180:183], v[196:199], v[56:59]
	v_mfma_f32_16x16x32_bf16 v[60:63], v[188:191], v[196:199], v[60:63]
	v_mfma_f32_16x16x32_bf16 v[48:51], v[180:183], v[218:221], v[48:51]
	v_mfma_f32_16x16x32_bf16 v[52:55], v[188:191], v[218:221], v[52:55]
	v_mfma_f32_16x16x32_bf16 v[40:43], v[180:183], v[226:229], v[40:43]
	v_mfma_f32_16x16x32_bf16 v[44:47], v[188:191], v[226:229], v[44:47]
	v_mfma_f32_16x16x32_bf16 v[32:35], v[180:183], v[234:237], v[32:35]
	v_mfma_f32_16x16x32_bf16 v[36:39], v[188:191], v[234:237], v[36:39]
	s_barrier
	s_add_i32 s20, s20, s50
	v_lshl_add_u64 v[166:167], s[10:11], 0, v[146:147]
	s_mov_b32 m0, s20
	ds_read_b128 v[192:195], v163 offset:16384
	ds_read_b128 v[196:199], v163 offset:17408
	ds_read_b128 v[214:217], v163 offset:18432
	ds_read_b128 v[218:221], v163 offset:19456
	ds_read_b128 v[222:225], v163 offset:20480
	ds_read_b128 v[226:229], v163 offset:21504
	ds_read_b128 v[230:233], v163 offset:22528
	ds_read_b128 v[234:237], v163 offset:23552
	global_load_lds_dwordx4 v[166:167], off
	s_add_i32 m0, s20, 0x2000
	s_add_u32 s20, s10, 0x40000
	v_lshl_add_u64 v[200:201], s[10:11], 0, v[150:151]
	s_addc_u32 s21, s11, 0
	s_add_i32 s53, s53, s50
	global_load_lds_dwordx4 v[200:201], off
	v_lshl_add_u64 v[238:239], s[20:21], 0, v[146:147]
	s_mov_b32 m0, s53
	v_lshl_add_u64 v[240:241], s[12:13], 0, v[148:149]
	global_load_lds_dwordx4 v[238:239], off
	v_lshl_add_u64 v[238:239], s[20:21], 0, v[150:151]
	s_add_i32 m0, s53, 0x2000
	s_nop 0
	global_load_lds_dwordx4 v[238:239], off
	v_lshl_add_u64 v[238:239], s[12:13], 0, v[144:145]
	s_mov_b32 m0, s51
	s_nop 0
	global_load_lds_dwordx4 v[238:239], off
	s_mov_b32 m0, s55
	s_nop 0
	global_load_lds_dwordx4 v[240:241], off
	s_waitcnt vmcnt(8)
	s_waitcnt lgkmcnt(0)
	s_barrier
; #define PG8_STAGE(bufoff, gbase, voff) do { _Pragma("unroll") for (int _i = 0; _i < 2; ++_i) \
;         __builtin_amdgcn_global_load_lds((const unsigned*)((const char*)(gbase) + (voff)[_i]), (PG8_LAS unsigned*)(lds + (bufoff) + ldsw + _i * 8192), 16, 0, 0); } while (0)
; #define PG8_LDA(dst, b, h) do { _Pragma("unroll") for (int m = 0; m < 4; ++m) _Pragma("unroll") for (int k = 0; k < 2; ++k) dst[m][k] = *(const PG8_LAS bf16x8*)(lds + PG8_SA(b, h) + aoff + m * 2048 + k * 1024); } while (0)
; #define PG8_LDB(dst, b, h) do { _Pragma("unroll") for (int n = 0; n < 2; ++n) _Pragma("unroll") for (int k = 0; k < 2; ++k) dst[n][k] = *(const PG8_LAS bf16x8*)(lds + PG8_SB(b, h) + boff + n * 2048 + k * 1024); } while (0)
; #define PG8_MMA(ai, bj, At, Bt) do { __builtin_amdgcn_s_setprio(1); _Pragma("unroll") for (int m = 0; m < 4; ++m) _Pragma("unroll") for (int n = 0; n < 2; ++n) _Pragma("unroll") for (int k = 0; k < 2; ++k) \
;         acc[ai][bj][m][n] = __builtin_amdgcn_mfma_f32_16x16x32_bf16(Bt[n][k], At[m][k], acc[ai][bj][m][n], 0, 0, 0); __builtin_amdgcn_s_setprio(0); } while (0)
; #define PG8_WAIT_V(n) asm volatile("s_waitcnt vmcnt(" #n ")" ::: "memory")
; #define PG8_BAR __builtin_amdgcn_s_barrier()
; template <class Epi, class Sched, bool ALIGN_EPI = false, bool SP2 = false>
; __device__ __forceinline__ void gemm_phase(PG8_LAS unsigned char* lds, const Gemm g, const Sched& S, const Epi& E, const int tid) {
;     ...
;         for (int t = 0; t < nt; t += 2) {
;             const bool last = (t == nt - 2);
;             const char* a1 = cA + (size_t)(t + 1) * kstep;
;             const char* a2 = last ? nA : cA + (size_t)(t + 2) * kstep; const char* b2 = last ? nB : cB + (size_t)(t + 2) * kstep;
;             const char* a3 = a2 + kstep; const char* b3 = b2 + kstep;
;             if (last && has_next) S.a_ready(nxt);
;             if constexpr (SP2) {
;             PG8_LDB(B0, 0, 0); PG8_LDB(B1, 0, 1); PG8_SCHED; PG8_LDA(At, 0, 0); PG8_STAGE(PG8_SA(1, 1), a1 + hstep, voffA);
;             PG8_WAIT_V(8); PG8_WAIT_L(0); PG8_BAR; PG8_MMA(0, 0, At, B0); PG8_MMA(0, 1, At, B1); PG8_BAR; PG8_SCHED;
;             PG8_LDA(At, 0, 1); PG8_STAGE(PG8_SB(0, 0), b2, voffB); PG8_STAGE(PG8_SB(0, 1), b2 + hstep, voffB); PG8_STAGE(PG8_SA(0, 0), a2, voffA);
;             PG8_WAIT_V(8); PG8_WAIT_L(0); PG8_BAR; PG8_MMA(1, 0, At, B0); PG8_MMA(1, 1, At, B1); PG8_BAR; PG8_SCHED;
	v_mfma_f32_16x16x32_bf16 v[88:91], v[128:131], v[192:195], 0
	v_mfma_f32_16x16x32_bf16 v[92:95], v[136:139], v[192:195], 0
	v_mfma_f32_16x16x32_bf16 v[80:83], v[128:131], v[214:217], 0
	v_mfma_f32_16x16x32_bf16 v[84:87], v[136:139], v[214:217], 0
	v_mfma_f32_16x16x32_bf16 v[72:75], v[128:131], v[222:225], 0
	v_mfma_f32_16x16x32_bf16 v[76:79], v[136:139], v[222:225], 0
	v_mfma_f32_16x16x32_bf16 v[64:67], v[128:131], v[230:233], 0
	v_mfma_f32_16x16x32_bf16 v[68:71], v[136:139], v[230:233], 0
	v_mfma_f32_16x16x32_bf16 v[88:91], v[132:135], v[196:199], v[88:91]
	v_mfma_f32_16x16x32_bf16 v[92:95], v[140:143], v[196:199], v[92:95]
	v_mfma_f32_16x16x32_bf16 v[80:83], v[132:135], v[218:221], v[80:83]
	v_mfma_f32_16x16x32_bf16 v[84:87], v[140:143], v[218:221], v[84:87]
	v_mfma_f32_16x16x32_bf16 v[72:75], v[132:135], v[226:229], v[72:75]
	v_mfma_f32_16x16x32_bf16 v[76:79], v[140:143], v[226:229], v[76:79]
	v_mfma_f32_16x16x32_bf16 v[64:67], v[132:135], v[234:237], v[64:67]
	v_mfma_f32_16x16x32_bf16 v[68:71], v[140:143], v[234:237], v[68:71]
	v_mfma_f32_16x16x32_bf16 v[24:27], v[156:159], v[192:195], 0
	v_mfma_f32_16x16x32_bf16 v[28:31], v[184:187], v[192:195], 0
	v_mfma_f32_16x16x32_bf16 v[16:19], v[156:159], v[214:217], 0
	v_mfma_f32_16x16x32_bf16 v[20:23], v[184:187], v[214:217], 0
	v_mfma_f32_16x16x32_bf16 v[8:11], v[156:159], v[222:225], 0
	v_mfma_f32_16x16x32_bf16 v[12:15], v[184:187], v[222:225], 0
	v_mfma_f32_16x16x32_bf16 v[4:7], v[156:159], v[230:233], 0
	v_mfma_f32_16x16x32_bf16 v[0:3], v[184:187], v[230:233], 0
	v_mfma_f32_16x16x32_bf16 v[24:27], v[180:183], v[196:199], v[24:27]
	v_mfma_f32_16x16x32_bf16 v[28:31], v[188:191], v[196:199], v[28:31]
	v_mfma_f32_16x16x32_bf16 v[16:19], v[180:183], v[218:221], v[16:19]
	v_mfma_f32_16x16x32_bf16 v[20:23], v[188:191], v[218:221], v[20:23]
	v_mfma_f32_16x16x32_bf16 v[8:11], v[180:183], v[226:229], v[8:11]
	v_mfma_f32_16x16x32_bf16 v[12:15], v[188:191], v[226:229], v[12:15]
	v_mfma_f32_16x16x32_bf16 v[4:7], v[180:183], v[234:237], v[4:7]
	v_mfma_f32_16x16x32_bf16 v[0:3], v[188:191], v[234:237], v[0:3]
	s_barrier
	s_branch .Lmix_mid
.LBB0_150:
	s_add_u32 s10, s2, 0xfffc0080
	s_addc_u32 s11, s3, -1
	s_add_i32 s20, 0, 0x10000
	s_cmp_eq_u32 s17, 12
	s_cselect_b32 s13, s1, s11
	s_cselect_b32 s12, s6, s10
	s_cselect_b32 s11, s7, s16
	s_cselect_b32 s10, s14, s15
	s_add_i32 s53, 0, 0x14000
	v_add_u32_e32 v140, s20, v162
	v_add_u32_e32 v164, s53, v162
	ds_read_b128 v[128:131], v140
	ds_read_b128 v[132:135], v140 offset:1024
	ds_read_b128 v[136:139], v140 offset:2048
	ds_read_b128 v[140:143], v140 offset:3072
	ds_read_b128 v[156:159], v164
	ds_read_b128 v[180:183], v164 offset:1024
	ds_read_b128 v[184:187], v164 offset:2048
	ds_read_b128 v[188:191], v164 offset:3072
	v_lshl_add_u64 v[166:167], s[2:3], 0, v[154:155]
	s_add_i32 m0, s51, 0xc000
	ds_read_b128 v[192:195], v163
	ds_read_b128 v[196:199], v163 offset:1024
	ds_read_b128 v[214:217], v163 offset:2048
	ds_read_b128 v[218:221], v163 offset:3072
	ds_read_b128 v[222:225], v163 offset:4096
	ds_read_b128 v[226:229], v163 offset:5120
	ds_read_b128 v[230:233], v163 offset:6144
	ds_read_b128 v[234:237], v163 offset:7168
	global_load_lds_dwordx4 v[166:167], off
	v_lshl_add_u64 v[166:167], s[2:3], 0, v[152:153]
	s_add_i32 m0, s51, 0xe000
	s_nop 0
	global_load_lds_dwordx4 v[166:167], off
	s_waitcnt vmcnt(8)
	s_waitcnt lgkmcnt(0)
	s_barrier
	v_mfma_f32_16x16x32_bf16 v[120:123], v[128:131], v[192:195], v[120:123]
	v_mfma_f32_16x16x32_bf16 v[124:127], v[136:139], v[192:195], v[124:127]
	v_mfma_f32_16x16x32_bf16 v[112:115], v[128:131], v[214:217], v[112:115]
	v_mfma_f32_16x16x32_bf16 v[116:119], v[136:139], v[214:217], v[116:119]
	v_mfma_f32_16x16x32_bf16 v[104:107], v[128:131], v[222:225], v[104:107]
	v_mfma_f32_16x16x32_bf16 v[108:111], v[136:139], v[222:225], v[108:111]
	v_mfma_f32_16x16x32_bf16 v[96:99], v[128:131], v[230:233], v[96:99]
	v_mfma_f32_16x16x32_bf16 v[100:103], v[136:139], v[230:233], v[100:103]
	v_mfma_f32_16x16x32_bf16 v[120:123], v[132:135], v[196:199], v[120:123]
	v_mfma_f32_16x16x32_bf16 v[124:127], v[140:143], v[196:199], v[124:127]
	v_mfma_f32_16x16x32_bf16 v[112:115], v[132:135], v[218:221], v[112:115]
	v_mfma_f32_16x16x32_bf16 v[116:119], v[140:143], v[218:221], v[116:119]
	v_mfma_f32_16x16x32_bf16 v[104:107], v[132:135], v[226:229], v[104:107]
	v_mfma_f32_16x16x32_bf16 v[108:111], v[140:143], v[226:229], v[108:111]
	v_mfma_f32_16x16x32_bf16 v[96:99], v[132:135], v[234:237], v[96:99]
	v_mfma_f32_16x16x32_bf16 v[100:103], v[140:143], v[234:237], v[100:103]
	v_mfma_f32_16x16x32_bf16 v[56:59], v[156:159], v[192:195], v[56:59]
	v_mfma_f32_16x16x32_bf16 v[60:63], v[184:187], v[192:195], v[60:63]
	v_mfma_f32_16x16x32_bf16 v[48:51], v[156:159], v[214:217], v[48:51]
	v_mfma_f32_16x16x32_bf16 v[52:55], v[184:187], v[214:217], v[52:55]
	v_mfma_f32_16x16x32_bf16 v[40:43], v[156:159], v[222:225], v[40:43]
	v_mfma_f32_16x16x32_bf16 v[44:47], v[184:187], v[222:225], v[44:47]
	v_mfma_f32_16x16x32_bf16 v[32:35], v[156:159], v[230:233], v[32:35]
	v_mfma_f32_16x16x32_bf16 v[36:39], v[184:187], v[230:233], v[36:39]
	v_mfma_f32_16x16x32_bf16 v[56:59], v[180:183], v[196:199], v[56:59]
	v_mfma_f32_16x16x32_bf16 v[60:63], v[188:191], v[196:199], v[60:63]
	v_mfma_f32_16x16x32_bf16 v[48:51], v[180:183], v[218:221], v[48:51]
	v_mfma_f32_16x16x32_bf16 v[52:55], v[188:191], v[218:221], v[52:55]
	v_mfma_f32_16x16x32_bf16 v[40:43], v[180:183], v[226:229], v[40:43]
	v_mfma_f32_16x16x32_bf16 v[44:47], v[188:191], v[226:229], v[44:47]
	v_mfma_f32_16x16x32_bf16 v[32:35], v[180:183], v[234:237], v[32:35]
	v_mfma_f32_16x16x32_bf16 v[36:39], v[188:191], v[234:237], v[36:39]
	s_barrier
; #define PG8_STAGE(bufoff, gbase, voff) do { _Pragma("unroll") for (int _i = 0; _i < 2; ++_i) \
;         __builtin_amdgcn_global_load_lds((const unsigned*)((const char*)(gbase) + (voff)[_i]), (PG8_LAS unsigned*)(lds + (bufoff) + ldsw + _i * 8192), 16, 0, 0); } while (0)
; #define PG8_LDA(dst, b, h) do { _Pragma("unroll") for (int m = 0; m < 4; ++m) _Pragma("unroll") for (int k = 0; k < 2; ++k) dst[m][k] = *(const PG8_LAS bf16x8*)(lds + PG8_SA(b, h) + aoff + m * 2048 + k * 1024); } while (0)
; #define PG8_LDB(dst, b, h) do { _Pragma("unroll") for (int n = 0; n < 2; ++n) _Pragma("unroll") for (int k = 0; k < 2; ++k) dst[n][k] = *(const PG8_LAS bf16x8*)(lds + PG8_SB(b, h) + boff + n * 2048 + k * 1024); } while (0)
; #define PG8_MMA(ai, bj, At, Bt) do { __builtin_amdgcn_s_setprio(1); _Pragma("unroll") for (int m = 0; m < 4; ++m) _Pragma("unroll") for (int n = 0; n < 2; ++n) _Pragma("unroll") for (int k = 0; k < 2; ++k) \
;         acc[ai][bj][m][n] = __builtin_amdgcn_mfma_f32_16x16x32_bf16(Bt[n][k], At[m][k], acc[ai][bj][m][n], 0, 0, 0); __builtin_amdgcn_s_setprio(0); } while (0)
; #define PG8_WAIT_V(n) asm volatile("s_waitcnt vmcnt(" #n ")" ::: "memory")
; #define PG8_WAIT_L(n) asm volatile("s_waitcnt lgkmcnt(" #n ")" ::: "memory")
; #define PG8_BAR __builtin_amdgcn_s_barrier()
; #define PG8_SCHED __builtin_amdgcn_sched_barrier(0)
; template <class Epi, class Sched, bool ALIGN_EPI = false, bool SP2 = false>
; __device__ __forceinline__ void gemm_phase(PG8_LAS unsigned char* lds, const Gemm g, const Sched& S, const Epi& E, const int tid) {
;     ...
;             PG8_LDA(At, 0, 1); PG8_STAGE(PG8_SB(0, 0), b2, voffB); PG8_STAGE(PG8_SB(0, 1), b2 + hstep, voffB); PG8_STAGE(PG8_SA(0, 0), a2, voffA);
;             PG8_WAIT_V(8); PG8_WAIT_L(0); PG8_BAR; PG8_MMA(1, 0, At, B0); PG8_MMA(1, 1, At, B1); PG8_BAR; PG8_SCHED;
;             PG8_LDB(B0, 1, 0); PG8_LDB(B1, 1, 1); PG8_SCHED; PG8_LDA(At, 1, 0); PG8_STAGE(PG8_SA(0, 1), a2 + hstep, voffA);
;             PG8_WAIT_V(8); PG8_WAIT_L(0); PG8_BAR; PG8_MMA(0, 0, At, B0); PG8_MMA(0, 1, At, B1); PG8_BAR; PG8_SCHED;
	s_add_i32 s20, s20, s50
	v_lshl_add_u64 v[166:167], s[10:11], 0, v[146:147]
	s_mov_b32 m0, s20
	ds_read_b128 v[192:195], v163 offset:16384
	ds_read_b128 v[196:199], v163 offset:17408
	ds_read_b128 v[214:217], v163 offset:18432
	ds_read_b128 v[218:221], v163 offset:19456
	ds_read_b128 v[222:225], v163 offset:20480
	ds_read_b128 v[226:229], v163 offset:21504
	ds_read_b128 v[230:233], v163 offset:22528
	ds_read_b128 v[234:237], v163 offset:23552
	global_load_lds_dwordx4 v[166:167], off
	s_add_i32 m0, s20, 0x2000
	s_add_u32 s20, s10, 0x40000
	v_lshl_add_u64 v[200:201], s[10:11], 0, v[150:151]
	s_addc_u32 s21, s11, 0
	s_add_i32 s53, s53, s50
	global_load_lds_dwordx4 v[200:201], off
	v_lshl_add_u64 v[238:239], s[20:21], 0, v[146:147]
	s_mov_b32 m0, s53
	v_lshl_add_u64 v[240:241], s[12:13], 0, v[148:149]
	global_load_lds_dwordx4 v[238:239], off
	v_lshl_add_u64 v[238:239], s[20:21], 0, v[150:151]
	s_add_i32 m0, s53, 0x2000
	s_nop 0
	global_load_lds_dwordx4 v[238:239], off
	v_lshl_add_u64 v[238:239], s[12:13], 0, v[144:145]
	s_mov_b32 m0, s51
	s_nop 0
	global_load_lds_dwordx4 v[238:239], off
	s_mov_b32 m0, s55
	s_nop 0
	global_load_lds_dwordx4 v[240:241], off
	s_waitcnt vmcnt(8)
	s_waitcnt lgkmcnt(0)
	s_barrier
	v_mfma_f32_16x16x32_bf16 v[88:91], v[128:131], v[192:195], v[88:91]
	v_mfma_f32_16x16x32_bf16 v[92:95], v[136:139], v[192:195], v[92:95]
	v_mfma_f32_16x16x32_bf16 v[80:83], v[128:131], v[214:217], v[80:83]
	v_mfma_f32_16x16x32_bf16 v[84:87], v[136:139], v[214:217], v[84:87]
	v_mfma_f32_16x16x32_bf16 v[72:75], v[128:131], v[222:225], v[72:75]
	v_mfma_f32_16x16x32_bf16 v[76:79], v[136:139], v[222:225], v[76:79]
	v_mfma_f32_16x16x32_bf16 v[64:67], v[128:131], v[230:233], v[64:67]
	v_mfma_f32_16x16x32_bf16 v[68:71], v[136:139], v[230:233], v[68:71]
	v_mfma_f32_16x16x32_bf16 v[88:91], v[132:135], v[196:199], v[88:91]
	v_mfma_f32_16x16x32_bf16 v[92:95], v[140:143], v[196:199], v[92:95]
	v_mfma_f32_16x16x32_bf16 v[80:83], v[132:135], v[218:221], v[80:83]
	v_mfma_f32_16x16x32_bf16 v[84:87], v[140:143], v[218:221], v[84:87]
	v_mfma_f32_16x16x32_bf16 v[72:75], v[132:135], v[226:229], v[72:75]
	v_mfma_f32_16x16x32_bf16 v[76:79], v[140:143], v[226:229], v[76:79]
	v_mfma_f32_16x16x32_bf16 v[64:67], v[132:135], v[234:237], v[64:67]
	v_mfma_f32_16x16x32_bf16 v[68:71], v[140:143], v[234:237], v[68:71]
	v_mfma_f32_16x16x32_bf16 v[24:27], v[156:159], v[192:195], v[24:27]
	v_mfma_f32_16x16x32_bf16 v[28:31], v[184:187], v[192:195], v[28:31]
	v_mfma_f32_16x16x32_bf16 v[16:19], v[156:159], v[214:217], v[16:19]
	v_mfma_f32_16x16x32_bf16 v[20:23], v[184:187], v[214:217], v[20:23]
	v_mfma_f32_16x16x32_bf16 v[8:11], v[156:159], v[222:225], v[8:11]
	v_mfma_f32_16x16x32_bf16 v[12:15], v[184:187], v[222:225], v[12:15]
	v_mfma_f32_16x16x32_bf16 v[4:7], v[156:159], v[230:233], v[4:7]
	v_mfma_f32_16x16x32_bf16 v[0:3], v[184:187], v[230:233], v[0:3]
	v_mfma_f32_16x16x32_bf16 v[24:27], v[180:183], v[196:199], v[24:27]
	v_mfma_f32_16x16x32_bf16 v[28:31], v[188:191], v[196:199], v[28:31]
	v_mfma_f32_16x16x32_bf16 v[16:19], v[180:183], v[218:221], v[16:19]
	v_mfma_f32_16x16x32_bf16 v[20:23], v[188:191], v[218:221], v[20:23]
	v_mfma_f32_16x16x32_bf16 v[8:11], v[180:183], v[226:229], v[8:11]
	v_mfma_f32_16x16x32_bf16 v[12:15], v[188:191], v[226:229], v[12:15]
	v_mfma_f32_16x16x32_bf16 v[4:7], v[180:183], v[234:237], v[4:7]
	v_mfma_f32_16x16x32_bf16 v[0:3], v[188:191], v[234:237], v[0:3]
	s_barrier
.Lmix_mid:
	s_add_i32 s20, 0, 0x18000
	s_add_i32 s21, 0, 0x1c000
	v_add_u32_e32 v140, s20, v162
	v_add_u32_e32 v164, s21, v162
	ds_read_b128 v[128:131], v140
	ds_read_b128 v[132:135], v140 offset:1024
	ds_read_b128 v[136:139], v140 offset:2048
	ds_read_b128 v[140:143], v140 offset:3072
	ds_read_b128 v[156:159], v164
	ds_read_b128 v[180:183], v164 offset:1024
	ds_read_b128 v[184:187], v164 offset:2048
	ds_read_b128 v[188:191], v164 offset:3072
	s_add_u32 s12, s12, 0x40000
	s_addc_u32 s13, s13, 0
	s_mov_b32 m0, s81
	v_lshl_add_u64 v[242:243], s[12:13], 0, v[144:145]
	ds_read_b128 v[192:195], v163 offset:32768
	ds_read_b128 v[196:199], v163 offset:33792
	ds_read_b128 v[214:217], v163 offset:34816
	ds_read_b128 v[218:221], v163 offset:35840
	ds_read_b128 v[222:225], v163 offset:36864
	ds_read_b128 v[226:229], v163 offset:37888
	ds_read_b128 v[230:233], v163 offset:38912
	ds_read_b128 v[234:237], v163 offset:39936
	global_load_lds_dwordx4 v[242:243], off
	v_lshl_add_u64 v[242:243], s[12:13], 0, v[148:149]
	s_mov_b32 m0, s38
	s_nop 0
	global_load_lds_dwordx4 v[242:243], off
	s_waitcnt vmcnt(8)
	s_waitcnt lgkmcnt(0)
	s_barrier
; #define PG8_STAGE(bufoff, gbase, voff) do { _Pragma("unroll") for (int _i = 0; _i < 2; ++_i) \
;         __builtin_amdgcn_global_load_lds((const unsigned*)((const char*)(gbase) + (voff)[_i]), (PG8_LAS unsigned*)(lds + (bufoff) + ldsw + _i * 8192), 16, 0, 0); } while (0)
; #define PG8_LDA(dst, b, h) do { _Pragma("unroll") for (int m = 0; m < 4; ++m) _Pragma("unroll") for (int k = 0; k < 2; ++k) dst[m][k] = *(const PG8_LAS bf16x8*)(lds + PG8_SA(b, h) + aoff + m * 2048 + k * 1024); } while (0)
; #define PG8_MMA(ai, bj, At, Bt) do { __builtin_amdgcn_s_setprio(1); _Pragma("unroll") for (int m = 0; m < 4; ++m) _Pragma("unroll") for (int n = 0; n < 2; ++n) _Pragma("unroll") for (int k = 0; k < 2; ++k) \
;         acc[ai][bj][m][n] = __builtin_amdgcn_mfma_f32_16x16x32_bf16(Bt[n][k], At[m][k], acc[ai][bj][m][n], 0, 0, 0); __builtin_amdgcn_s_setprio(0); } while (0)
; #define PG8_WAIT_V(n) asm volatile("s_waitcnt vmcnt(" #n ")" ::: "memory")
; #define PG8_WAIT_L(n) asm volatile("s_waitcnt lgkmcnt(" #n ")" ::: "memory")
; #define PG8_BAR __builtin_amdgcn_s_barrier()
; #define PG8_SCHED __builtin_amdgcn_sched_barrier(0)
; template <class Epi, class Sched, bool ALIGN_EPI = false, bool SP2 = false>
; __device__ __forceinline__ void gemm_phase(PG8_LAS unsigned char* lds, const Gemm g, const Sched& S, const Epi& E, const int tid) {
;     ...
;             PG8_WAIT_V(8); PG8_WAIT_L(0); PG8_BAR; PG8_MMA(0, 0, At, B0); PG8_MMA(0, 1, At, B1); PG8_BAR; PG8_SCHED;
;             PG8_LDA(At, 1, 1); PG8_STAGE(PG8_SB(1, 0), b3, voffB); PG8_STAGE(PG8_SB(1, 1), b3 + hstep, voffB); PG8_STAGE(PG8_SA(1, 0), a3, voffA);
;             PG8_WAIT_V(8); PG8_WAIT_L(0); PG8_BAR; PG8_MMA(1, 0, At, B0); PG8_MMA(1, 1, At, B1); PG8_BAR; PG8_SCHED;
;     ...
;         if constexpr (ALIGN_EPI) { if (wr == 0) PG8_BAR; }
	v_mfma_f32_16x16x32_bf16 v[120:123], v[128:131], v[192:195], v[120:123]
	v_mfma_f32_16x16x32_bf16 v[124:127], v[136:139], v[192:195], v[124:127]
	v_mfma_f32_16x16x32_bf16 v[112:115], v[128:131], v[214:217], v[112:115]
	v_mfma_f32_16x16x32_bf16 v[116:119], v[136:139], v[214:217], v[116:119]
	v_mfma_f32_16x16x32_bf16 v[104:107], v[128:131], v[222:225], v[104:107]
	v_mfma_f32_16x16x32_bf16 v[108:111], v[136:139], v[222:225], v[108:111]
	v_mfma_f32_16x16x32_bf16 v[96:99], v[128:131], v[230:233], v[96:99]
	v_mfma_f32_16x16x32_bf16 v[100:103], v[136:139], v[230:233], v[100:103]
	v_mfma_f32_16x16x32_bf16 v[120:123], v[132:135], v[196:199], v[120:123]
	v_mfma_f32_16x16x32_bf16 v[124:127], v[140:143], v[196:199], v[124:127]
	v_mfma_f32_16x16x32_bf16 v[112:115], v[132:135], v[218:221], v[112:115]
	v_mfma_f32_16x16x32_bf16 v[116:119], v[140:143], v[218:221], v[116:119]
	v_mfma_f32_16x16x32_bf16 v[104:107], v[132:135], v[226:229], v[104:107]
	v_mfma_f32_16x16x32_bf16 v[108:111], v[140:143], v[226:229], v[108:111]
	v_mfma_f32_16x16x32_bf16 v[96:99], v[132:135], v[234:237], v[96:99]
	v_mfma_f32_16x16x32_bf16 v[100:103], v[140:143], v[234:237], v[100:103]
	v_mfma_f32_16x16x32_bf16 v[56:59], v[156:159], v[192:195], v[56:59]
	v_mfma_f32_16x16x32_bf16 v[60:63], v[184:187], v[192:195], v[60:63]
	v_mfma_f32_16x16x32_bf16 v[48:51], v[156:159], v[214:217], v[48:51]
	v_mfma_f32_16x16x32_bf16 v[52:55], v[184:187], v[214:217], v[52:55]
	v_mfma_f32_16x16x32_bf16 v[40:43], v[156:159], v[222:225], v[40:43]
	v_mfma_f32_16x16x32_bf16 v[44:47], v[184:187], v[222:225], v[44:47]
	v_mfma_f32_16x16x32_bf16 v[32:35], v[156:159], v[230:233], v[32:35]
	v_mfma_f32_16x16x32_bf16 v[36:39], v[184:187], v[230:233], v[36:39]
	v_mfma_f32_16x16x32_bf16 v[56:59], v[180:183], v[196:199], v[56:59]
	v_mfma_f32_16x16x32_bf16 v[60:63], v[188:191], v[196:199], v[60:63]
	v_mfma_f32_16x16x32_bf16 v[48:51], v[180:183], v[218:221], v[48:51]
	v_mfma_f32_16x16x32_bf16 v[52:55], v[188:191], v[218:221], v[52:55]
	v_mfma_f32_16x16x32_bf16 v[40:43], v[180:183], v[226:229], v[40:43]
	v_mfma_f32_16x16x32_bf16 v[44:47], v[188:191], v[226:229], v[44:47]
	v_mfma_f32_16x16x32_bf16 v[32:35], v[180:183], v[234:237], v[32:35]
	v_mfma_f32_16x16x32_bf16 v[36:39], v[188:191], v[234:237], v[36:39]
	s_barrier
	s_add_i32 s12, s20, s50
	v_lshl_add_u64 v[166:167], v[166:167], 0, s[86:87]
	s_mov_b32 m0, s12
	ds_read_b128 v[192:195], v163 offset:49152
	ds_read_b128 v[196:199], v163 offset:50176
	ds_read_b128 v[214:217], v163 offset:51200
	ds_read_b128 v[218:221], v163 offset:52224
	ds_read_b128 v[222:225], v163 offset:53248
	ds_read_b128 v[226:229], v163 offset:54272
	ds_read_b128 v[230:233], v163 offset:55296
	ds_read_b128 v[234:237], v163 offset:56320
	global_load_lds_dwordx4 v[166:167], off
	s_add_i32 m0, s12, 0x2000
	s_add_u32 s10, s10, 0x40080
	v_lshl_add_u64 v[166:167], v[200:201], 0, s[86:87]
	s_addc_u32 s11, s11, 0
	s_add_i32 s12, s21, s50
	global_load_lds_dwordx4 v[166:167], off
	v_lshl_add_u64 v[166:167], s[10:11], 0, v[146:147]
	s_mov_b32 m0, s12
	s_nop 0
	global_load_lds_dwordx4 v[166:167], off
	v_lshl_add_u64 v[166:167], s[10:11], 0, v[150:151]
	s_add_i32 m0, s12, 0x2000
	s_nop 0
	global_load_lds_dwordx4 v[166:167], off
	v_lshl_add_u64 v[166:167], v[238:239], 0, s[86:87]
	s_mov_b32 m0, s37
	s_nop 0
	global_load_lds_dwordx4 v[166:167], off
	v_lshl_add_u64 v[166:167], v[240:241], 0, s[86:87]
	s_mov_b32 m0, s41
	s_nop 0
	global_load_lds_dwordx4 v[166:167], off
	s_waitcnt vmcnt(8)
	s_waitcnt lgkmcnt(0)
	s_barrier
	v_mfma_f32_16x16x32_bf16 v[88:91], v[128:131], v[192:195], v[88:91]
	v_mfma_f32_16x16x32_bf16 v[92:95], v[136:139], v[192:195], v[92:95]
	v_mfma_f32_16x16x32_bf16 v[80:83], v[128:131], v[214:217], v[80:83]
	v_mfma_f32_16x16x32_bf16 v[84:87], v[136:139], v[214:217], v[84:87]
	v_mfma_f32_16x16x32_bf16 v[72:75], v[128:131], v[222:225], v[72:75]
	v_mfma_f32_16x16x32_bf16 v[76:79], v[136:139], v[222:225], v[76:79]
	v_mfma_f32_16x16x32_bf16 v[64:67], v[128:131], v[230:233], v[64:67]
	v_mfma_f32_16x16x32_bf16 v[68:71], v[136:139], v[230:233], v[68:71]
	v_mfma_f32_16x16x32_bf16 v[88:91], v[132:135], v[196:199], v[88:91]
	v_mfma_f32_16x16x32_bf16 v[92:95], v[140:143], v[196:199], v[92:95]
	v_mfma_f32_16x16x32_bf16 v[80:83], v[132:135], v[218:221], v[80:83]
	v_mfma_f32_16x16x32_bf16 v[84:87], v[140:143], v[218:221], v[84:87]
	v_mfma_f32_16x16x32_bf16 v[72:75], v[132:135], v[226:229], v[72:75]
	v_mfma_f32_16x16x32_bf16 v[76:79], v[140:143], v[226:229], v[76:79]
	v_mfma_f32_16x16x32_bf16 v[64:67], v[132:135], v[234:237], v[64:67]
	v_mfma_f32_16x16x32_bf16 v[68:71], v[140:143], v[234:237], v[68:71]
	v_mfma_f32_16x16x32_bf16 v[24:27], v[156:159], v[192:195], v[24:27]
	v_mfma_f32_16x16x32_bf16 v[28:31], v[184:187], v[192:195], v[28:31]
	v_mfma_f32_16x16x32_bf16 v[16:19], v[156:159], v[214:217], v[16:19]
	v_mfma_f32_16x16x32_bf16 v[20:23], v[184:187], v[214:217], v[20:23]
	v_mfma_f32_16x16x32_bf16 v[8:11], v[156:159], v[222:225], v[8:11]
	v_mfma_f32_16x16x32_bf16 v[12:15], v[184:187], v[222:225], v[12:15]
	v_mfma_f32_16x16x32_bf16 v[4:7], v[156:159], v[230:233], v[4:7]
	v_mfma_f32_16x16x32_bf16 v[0:3], v[184:187], v[230:233], v[0:3]
	v_mfma_f32_16x16x32_bf16 v[24:27], v[180:183], v[196:199], v[24:27]
	v_mfma_f32_16x16x32_bf16 v[28:31], v[188:191], v[196:199], v[28:31]
	v_mfma_f32_16x16x32_bf16 v[16:19], v[180:183], v[218:221], v[16:19]
	v_mfma_f32_16x16x32_bf16 v[20:23], v[188:191], v[218:221], v[20:23]
	v_mfma_f32_16x16x32_bf16 v[8:11], v[180:183], v[226:229], v[8:11]
	v_mfma_f32_16x16x32_bf16 v[12:15], v[188:191], v[226:229], v[12:15]
	v_mfma_f32_16x16x32_bf16 v[4:7], v[180:183], v[234:237], v[4:7]
	v_mfma_f32_16x16x32_bf16 v[0:3], v[188:191], v[234:237], v[0:3]
	s_barrier
	s_add_i32 s17, s17, 2
	s_add_u32 s15, s15, 0x100
	s_addc_u32 s16, s16, 0
	s_add_u32 s2, s2, 0x100
	s_addc_u32 s3, s3, 0
	s_cmp_gt_u32 s17, 13
	s_cbranch_scc0 .LBB0_150
	v_readlane_b32 s2, v255, 13
	v_readlane_b32 s3, v255, 14
	s_and_b64 vcc, exec, s[2:3]
	s_cbranch_vccz .LBB0_153
	s_barrier

; #define PG8_STAGE(bufoff, gbase, voff) do { _Pragma("unroll") for (int _i = 0; _i < 2; ++_i) \
;         __builtin_amdgcn_global_load_lds((const unsigned*)((const char*)(gbase) + (voff)[_i]), (PG8_LAS unsigned*)(lds + (bufoff) + ldsw + _i * 8192), 16, 0, 0); } while (0)
; #define PG8_LDA(dst, b, h) do { _Pragma("unroll") for (int m = 0; m < 4; ++m) _Pragma("unroll") for (int k = 0; k < 2; ++k) dst[m][k] = *(const PG8_LAS bf16x8*)(lds + PG8_SA(b, h) + aoff + m * 2048 + k * 1024); } while (0)
; #define PG8_LDB(dst, b, h) do { _Pragma("unroll") for (int n = 0; n < 2; ++n) _Pragma("unroll") for (int k = 0; k < 2; ++k) dst[n][k] = *(const PG8_LAS bf16x8*)(lds + PG8_SB(b, h) + boff + n * 2048 + k * 1024); } while (0)
; #define PG8_WAIT_V(n) asm volatile("s_waitcnt vmcnt(" #n ")" ::: "memory")
; #define PG8_WAIT_L(n) asm volatile("s_waitcnt lgkmcnt(" #n ")" ::: "memory")
; #define PG8_BAR __builtin_amdgcn_s_barrier()
; #define PG8_SCHED __builtin_amdgcn_sched_barrier(0)
; template <class Epi, class Sched, bool ALIGN_EPI = false, bool SP2 = false>
; __device__ __forceinline__ void gemm_phase(PG8_LAS unsigned char* lds, const Gemm g, const Sched& S, const Epi& E, const int tid) {
;     ...
;         const bool has_next = S.next(ui + 1, nxt);
;         const char* nA = has_next ? (const char*)g.A + (size_t)nxt.pm * tstep : cA; const char* nB = has_next ? (const char*)g.Bt + (size_t)nxt.pn * tstep : cB;
;         for (int t = 0; t < nt; t += 2) {
;             const bool last = (t == nt - 2);
;             const char* a1 = cA + (size_t)(t + 1) * kstep;
;             const char* a2 = last ? nA : cA + (size_t)(t + 2) * kstep; const char* b2 = last ? nB : cB + (size_t)(t + 2) * kstep;
;             const char* a3 = a2 + kstep; const char* b3 = b2 + kstep;
;             if (last && has_next) S.a_ready(nxt);
;             if constexpr (SP2) {
;             PG8_LDB(B0, 0, 0); PG8_LDB(B1, 0, 1); PG8_SCHED; PG8_LDA(At, 0, 0); PG8_STAGE(PG8_SA(1, 1), a1 + hstep, voffA);
;             PG8_WAIT_V(8); PG8_WAIT_L(0); PG8_BAR; PG8_MMA(0, 0, At, B0); PG8_MMA(0, 1, At, B1); PG8_BAR; PG8_SCHED;
;             PG8_LDA(At, 0, 1); PG8_STAGE(PG8_SB(0, 0), b2, voffB); PG8_STAGE(PG8_SB(0, 1), b2 + hstep, voffB); PG8_STAGE(PG8_SA(0, 0), a2, voffA);
;             PG8_WAIT_V(8); PG8_WAIT_L(0); PG8_BAR; PG8_MMA(1, 0, At, B0); PG8_MMA(1, 1, At, B1); PG8_BAR; PG8_SCHED;
.LBB0_1304:
	s_add_u32 s73, s8, 0x100
	s_addc_u32 s81, s9, 0
	s_add_u32 s8, s54, 0x80
	s_addc_u32 s9, s55, 0
	s_mov_b32 s54, 0
	s_add_i32 s84, s54, 2
	s_add_u32 s85, s8, 0x80
	s_addc_u32 s55, s9, 0
	s_add_i32 s82, 0, 0x10000
	s_cmp_eq_u32 s62, s54
	s_cselect_b32 s55, s1, s55
	s_cselect_b32 s54, s0, s85
	s_cselect_b32 vcc_hi, s21, s81
	s_cselect_b32 vcc_lo, s20, s73
	s_add_i32 s85, 0, 0x14000
	v_add_u32_e32 v52, s82, v181
	v_add_u32_e32 v156, s85, v181
	ds_read_b128 v[32:35], v52
	ds_read_b128 v[36:39], v52 offset:1024
	ds_read_b128 v[48:51], v52 offset:2048
	ds_read_b128 v[52:55], v52 offset:3072
	ds_read_b128 v[144:147], v156
	ds_read_b128 v[148:151], v156 offset:1024
	ds_read_b128 v[152:155], v156 offset:2048
	ds_read_b128 v[156:159], v156 offset:3072
	v_lshl_add_u64 v[200:201], s[8:9], 0, v[186:187]
	s_add_i32 m0, s45, 0xc000
	ds_read_b128 v[188:191], v218
	ds_read_b128 v[192:195], v218 offset:1024
	ds_read_b128 v[196:199], v218 offset:2048
	ds_read_b128 v[222:225], v218 offset:3072
	ds_read_b128 v[226:229], v218 offset:4096
	ds_read_b128 v[230:233], v218 offset:5120
	ds_read_b128 v[234:237], v218 offset:6144
	ds_read_b128 v[238:241], v218 offset:7168
	global_load_lds_dwordx4 v[200:201], off
	v_lshl_add_u64 v[200:201], s[8:9], 0, v[184:185]
	s_add_i32 m0, s45, 0xe000
	s_nop 0
	global_load_lds_dwordx4 v[200:201], off
	s_waitcnt vmcnt(8)
	s_waitcnt lgkmcnt(0)
	s_barrier
	v_mfma_f32_16x16x32_bf16 v[140:143], v[32:35], v[188:191], 0
	v_mfma_f32_16x16x32_bf16 v[136:139], v[48:51], v[188:191], 0
	v_mfma_f32_16x16x32_bf16 v[124:127], v[32:35], v[196:199], 0
	v_mfma_f32_16x16x32_bf16 v[120:123], v[48:51], v[196:199], 0
	v_mfma_f32_16x16x32_bf16 v[108:111], v[32:35], v[226:229], 0
	v_mfma_f32_16x16x32_bf16 v[104:107], v[48:51], v[226:229], 0
	v_mfma_f32_16x16x32_bf16 v[92:95], v[32:35], v[234:237], 0
	v_mfma_f32_16x16x32_bf16 v[88:91], v[48:51], v[234:237], 0
	v_mfma_f32_16x16x32_bf16 v[140:143], v[36:39], v[192:195], v[140:143]
	v_mfma_f32_16x16x32_bf16 v[136:139], v[52:55], v[192:195], v[136:139]
	v_mfma_f32_16x16x32_bf16 v[124:127], v[36:39], v[222:225], v[124:127]
	v_mfma_f32_16x16x32_bf16 v[120:123], v[52:55], v[222:225], v[120:123]
	v_mfma_f32_16x16x32_bf16 v[108:111], v[36:39], v[230:233], v[108:111]
	v_mfma_f32_16x16x32_bf16 v[104:107], v[52:55], v[230:233], v[104:107]
	v_mfma_f32_16x16x32_bf16 v[92:95], v[36:39], v[238:241], v[92:95]
	v_mfma_f32_16x16x32_bf16 v[88:91], v[52:55], v[238:241], v[88:91]
	v_mfma_f32_16x16x32_bf16 v[132:135], v[144:147], v[188:191], 0
	v_mfma_f32_16x16x32_bf16 v[128:131], v[152:155], v[188:191], 0
	v_mfma_f32_16x16x32_bf16 v[116:119], v[144:147], v[196:199], 0
	v_mfma_f32_16x16x32_bf16 v[112:115], v[152:155], v[196:199], 0
	v_mfma_f32_16x16x32_bf16 v[100:103], v[144:147], v[226:229], 0
	v_mfma_f32_16x16x32_bf16 v[96:99], v[152:155], v[226:229], 0
	v_mfma_f32_16x16x32_bf16 v[84:87], v[144:147], v[234:237], 0
	v_mfma_f32_16x16x32_bf16 v[80:83], v[152:155], v[234:237], 0
	v_mfma_f32_16x16x32_bf16 v[132:135], v[148:151], v[192:195], v[132:135]
	v_mfma_f32_16x16x32_bf16 v[128:131], v[156:159], v[192:195], v[128:131]
	v_mfma_f32_16x16x32_bf16 v[116:119], v[148:151], v[222:225], v[116:119]
	v_mfma_f32_16x16x32_bf16 v[112:115], v[156:159], v[222:225], v[112:115]
	v_mfma_f32_16x16x32_bf16 v[100:103], v[148:151], v[230:233], v[100:103]
	v_mfma_f32_16x16x32_bf16 v[96:99], v[156:159], v[230:233], v[96:99]
	v_mfma_f32_16x16x32_bf16 v[84:87], v[148:151], v[238:241], v[84:87]
	v_mfma_f32_16x16x32_bf16 v[80:83], v[156:159], v[238:241], v[80:83]
	s_barrier
	s_add_i32 s82, s82, s38
	v_lshl_add_u64 v[200:201], vcc, 0, v[164:165]
	s_mov_b32 m0, s82
	ds_read_b128 v[188:191], v218 offset:16384
	ds_read_b128 v[192:195], v218 offset:17408
	ds_read_b128 v[196:199], v218 offset:18432
	ds_read_b128 v[222:225], v218 offset:19456
	ds_read_b128 v[226:229], v218 offset:20480
	ds_read_b128 v[230:233], v218 offset:21504
	ds_read_b128 v[234:237], v218 offset:22528
	ds_read_b128 v[238:241], v218 offset:23552
	global_load_lds_dwordx4 v[200:201], off
	s_add_i32 m0, s82, 0x2000
	v_lshl_add_u64 v[242:243], vcc, 0, v[160:161]
	s_add_u32 vcc_lo, vcc_lo, s90
	s_addc_u32 vcc_hi, vcc_hi, 0
	s_add_i32 s82, s85, s38
	global_load_lds_dwordx4 v[242:243], off
	v_lshl_add_u64 v[244:245], vcc, 0, v[164:165]
	s_mov_b32 m0, s82
	v_lshl_add_u64 v[246:247], vcc, 0, v[160:161]
	global_load_lds_dwordx4 v[244:245], off
	s_add_i32 m0, s82, 0x2000
	v_lshl_add_u64 v[248:249], s[54:55], 0, v[164:165]
	global_load_lds_dwordx4 v[246:247], off
	s_mov_b32 m0, s45
	v_lshl_add_u64 v[250:251], s[54:55], 0, v[160:161]
	global_load_lds_dwordx4 v[248:249], off
	s_mov_b32 m0, s48
	s_nop 0
	global_load_lds_dwordx4 v[250:251], off
	s_waitcnt vmcnt(8)
	s_waitcnt lgkmcnt(0)
	s_barrier
	v_mfma_f32_16x16x32_bf16 v[76:79], v[32:35], v[188:191], 0
	v_mfma_f32_16x16x32_bf16 v[72:75], v[48:51], v[188:191], 0
	v_mfma_f32_16x16x32_bf16 v[60:63], v[32:35], v[196:199], 0
	v_mfma_f32_16x16x32_bf16 v[56:59], v[48:51], v[196:199], 0
	v_mfma_f32_16x16x32_bf16 v[28:31], v[32:35], v[226:229], 0
	v_mfma_f32_16x16x32_bf16 v[24:27], v[48:51], v[226:229], 0
	v_mfma_f32_16x16x32_bf16 v[12:15], v[32:35], v[234:237], 0
	v_mfma_f32_16x16x32_bf16 v[8:11], v[48:51], v[234:237], 0
	v_mfma_f32_16x16x32_bf16 v[76:79], v[36:39], v[192:195], v[76:79]
	v_mfma_f32_16x16x32_bf16 v[72:75], v[52:55], v[192:195], v[72:75]
	v_mfma_f32_16x16x32_bf16 v[60:63], v[36:39], v[222:225], v[60:63]
	v_mfma_f32_16x16x32_bf16 v[56:59], v[52:55], v[222:225], v[56:59]
	v_mfma_f32_16x16x32_bf16 v[28:31], v[36:39], v[230:233], v[28:31]
	v_mfma_f32_16x16x32_bf16 v[24:27], v[52:55], v[230:233], v[24:27]
	v_mfma_f32_16x16x32_bf16 v[12:15], v[36:39], v[238:241], v[12:15]
	v_mfma_f32_16x16x32_bf16 v[8:11], v[52:55], v[238:241], v[8:11]
	v_mfma_f32_16x16x32_bf16 v[44:47], v[144:147], v[196:199], 0
	v_mfma_f32_16x16x32_bf16 v[40:43], v[152:155], v[196:199], 0
	v_mfma_f32_16x16x32_bf16 v[20:23], v[144:147], v[226:229], 0
	v_mfma_f32_16x16x32_bf16 v[16:19], v[152:155], v[226:229], 0
	v_mfma_f32_16x16x32_bf16 v[4:7], v[144:147], v[234:237], 0
	v_mfma_f32_16x16x32_bf16 v[0:3], v[152:155], v[234:237], 0
	v_mfma_f32_16x16x32_bf16 v[32:35], v[144:147], v[188:191], 0
	v_mfma_f32_16x16x32_bf16 v[36:39], v[152:155], v[188:191], 0
	v_mfma_f32_16x16x32_bf16 v[44:47], v[148:151], v[222:225], v[44:47]
	v_mfma_f32_16x16x32_bf16 v[40:43], v[156:159], v[222:225], v[40:43]
	v_mfma_f32_16x16x32_bf16 v[20:23], v[148:151], v[230:233], v[20:23]
	v_mfma_f32_16x16x32_bf16 v[16:19], v[156:159], v[230:233], v[16:19]
	v_mfma_f32_16x16x32_bf16 v[4:7], v[148:151], v[238:241], v[4:7]
	v_mfma_f32_16x16x32_bf16 v[0:3], v[156:159], v[238:241], v[0:3]
	v_mfma_f32_16x16x32_bf16 v[32:35], v[148:151], v[192:195], v[32:35]
	v_mfma_f32_16x16x32_bf16 v[36:39], v[156:159], v[192:195], v[36:39]
	s_barrier
	s_branch .Lres_mid
; #define PG8_STAGE(bufoff, gbase, voff) do { _Pragma("unroll") for (int _i = 0; _i < 2; ++_i) \
;         __builtin_amdgcn_global_load_lds((const unsigned*)((const char*)(gbase) + (voff)[_i]), (PG8_LAS unsigned*)(lds + (bufoff) + ldsw + _i * 8192), 16, 0, 0); } while (0)
; #define PG8_LDA(dst, b, h) do { _Pragma("unroll") for (int m = 0; m < 4; ++m) _Pragma("unroll") for (int k = 0; k < 2; ++k) dst[m][k] = *(const PG8_LAS bf16x8*)(lds + PG8_SA(b, h) + aoff + m * 2048 + k * 1024); } while (0)
; #define PG8_LDB(dst, b, h) do { _Pragma("unroll") for (int n = 0; n < 2; ++n) _Pragma("unroll") for (int k = 0; k < 2; ++k) dst[n][k] = *(const PG8_LAS bf16x8*)(lds + PG8_SB(b, h) + boff + n * 2048 + k * 1024); } while (0)
; #define PG8_MMA(ai, bj, At, Bt) do { __builtin_amdgcn_s_setprio(1); _Pragma("unroll") for (int m = 0; m < 4; ++m) _Pragma("unroll") for (int n = 0; n < 2; ++n) _Pragma("unroll") for (int k = 0; k < 2; ++k) \
;         acc[ai][bj][m][n] = __builtin_amdgcn_mfma_f32_16x16x32_bf16(Bt[n][k], At[m][k], acc[ai][bj][m][n], 0, 0, 0); __builtin_amdgcn_s_setprio(0); } while (0)
; #define PG8_WAIT_V(n) asm volatile("s_waitcnt vmcnt(" #n ")" ::: "memory")
; #define PG8_WAIT_L(n) asm volatile("s_waitcnt lgkmcnt(" #n ")" ::: "memory")
; #define PG8_BAR __builtin_amdgcn_s_barrier()
; #define PG8_SCHED __builtin_amdgcn_sched_barrier(0)
; template <class Epi, class Sched, bool ALIGN_EPI = false, bool SP2 = false>
; __device__ __forceinline__ void gemm_phase(PG8_LAS unsigned char* lds, const Gemm g, const Sched& S, const Epi& E, const int tid) {
;     ...
;             PG8_LDB(B0, 0, 0); PG8_LDB(B1, 0, 1); PG8_SCHED; PG8_LDA(At, 0, 0); PG8_STAGE(PG8_SA(1, 1), a1 + hstep, voffA);
;             PG8_WAIT_V(8); PG8_WAIT_L(0); PG8_BAR; PG8_MMA(0, 0, At, B0); PG8_MMA(0, 1, At, B1); PG8_BAR; PG8_SCHED;
;             PG8_LDA(At, 0, 1); PG8_STAGE(PG8_SB(0, 0), b2, voffB); PG8_STAGE(PG8_SB(0, 1), b2 + hstep, voffB); PG8_STAGE(PG8_SA(0, 0), a2, voffA);
;             PG8_WAIT_V(8); PG8_WAIT_L(0); PG8_BAR; PG8_MMA(1, 0, At, B0); PG8_MMA(1, 1, At, B1); PG8_BAR; PG8_SCHED;
.LBB0_1305:
	s_add_i32 s84, s54, 2
	s_add_u32 s85, s8, 0x80
	s_addc_u32 s55, s9, 0
	s_add_i32 s82, 0, 0x10000
	s_cmp_eq_u32 s62, s54
	s_cselect_b32 s55, s1, s55
	s_cselect_b32 s54, s0, s85
	s_cselect_b32 vcc_hi, s21, s81
	s_cselect_b32 vcc_lo, s20, s73
	s_add_i32 s85, 0, 0x14000
	v_add_u32_e32 v52, s82, v181
	v_add_u32_e32 v156, s85, v181
	ds_read_b128 v[32:35], v52
	ds_read_b128 v[36:39], v52 offset:1024
	ds_read_b128 v[48:51], v52 offset:2048
	ds_read_b128 v[52:55], v52 offset:3072
	ds_read_b128 v[144:147], v156
	ds_read_b128 v[148:151], v156 offset:1024
	ds_read_b128 v[152:155], v156 offset:2048
	ds_read_b128 v[156:159], v156 offset:3072
	v_lshl_add_u64 v[200:201], s[8:9], 0, v[186:187]
	s_add_i32 m0, s45, 0xc000
	ds_read_b128 v[188:191], v218
	ds_read_b128 v[192:195], v218 offset:1024
	ds_read_b128 v[196:199], v218 offset:2048
	ds_read_b128 v[222:225], v218 offset:3072
	ds_read_b128 v[226:229], v218 offset:4096
	ds_read_b128 v[230:233], v218 offset:5120
	ds_read_b128 v[234:237], v218 offset:6144
	ds_read_b128 v[238:241], v218 offset:7168
	global_load_lds_dwordx4 v[200:201], off
	v_lshl_add_u64 v[200:201], s[8:9], 0, v[184:185]
	s_add_i32 m0, s45, 0xe000
	s_nop 0
	global_load_lds_dwordx4 v[200:201], off
	s_waitcnt vmcnt(8)
	s_waitcnt lgkmcnt(0)
	s_barrier
	v_mfma_f32_16x16x32_bf16 v[140:143], v[32:35], v[188:191], v[140:143]
	v_mfma_f32_16x16x32_bf16 v[136:139], v[48:51], v[188:191], v[136:139]
	v_mfma_f32_16x16x32_bf16 v[124:127], v[32:35], v[196:199], v[124:127]
	v_mfma_f32_16x16x32_bf16 v[120:123], v[48:51], v[196:199], v[120:123]
	v_mfma_f32_16x16x32_bf16 v[108:111], v[32:35], v[226:229], v[108:111]
	v_mfma_f32_16x16x32_bf16 v[104:107], v[48:51], v[226:229], v[104:107]
	v_mfma_f32_16x16x32_bf16 v[92:95], v[32:35], v[234:237], v[92:95]
	v_mfma_f32_16x16x32_bf16 v[88:91], v[48:51], v[234:237], v[88:91]
	v_mfma_f32_16x16x32_bf16 v[140:143], v[36:39], v[192:195], v[140:143]
	v_mfma_f32_16x16x32_bf16 v[136:139], v[52:55], v[192:195], v[136:139]
	v_mfma_f32_16x16x32_bf16 v[124:127], v[36:39], v[222:225], v[124:127]
	v_mfma_f32_16x16x32_bf16 v[120:123], v[52:55], v[222:225], v[120:123]
	v_mfma_f32_16x16x32_bf16 v[108:111], v[36:39], v[230:233], v[108:111]
	v_mfma_f32_16x16x32_bf16 v[104:107], v[52:55], v[230:233], v[104:107]
	v_mfma_f32_16x16x32_bf16 v[92:95], v[36:39], v[238:241], v[92:95]
	v_mfma_f32_16x16x32_bf16 v[88:91], v[52:55], v[238:241], v[88:91]
	v_mfma_f32_16x16x32_bf16 v[132:135], v[144:147], v[188:191], v[132:135]
	v_mfma_f32_16x16x32_bf16 v[128:131], v[152:155], v[188:191], v[128:131]
	v_mfma_f32_16x16x32_bf16 v[116:119], v[144:147], v[196:199], v[116:119]
	v_mfma_f32_16x16x32_bf16 v[112:115], v[152:155], v[196:199], v[112:115]
	v_mfma_f32_16x16x32_bf16 v[100:103], v[144:147], v[226:229], v[100:103]
	v_mfma_f32_16x16x32_bf16 v[96:99], v[152:155], v[226:229], v[96:99]
	v_mfma_f32_16x16x32_bf16 v[84:87], v[144:147], v[234:237], v[84:87]
	v_mfma_f32_16x16x32_bf16 v[80:83], v[152:155], v[234:237], v[80:83]
	v_mfma_f32_16x16x32_bf16 v[132:135], v[148:151], v[192:195], v[132:135]
	v_mfma_f32_16x16x32_bf16 v[128:131], v[156:159], v[192:195], v[128:131]
	v_mfma_f32_16x16x32_bf16 v[116:119], v[148:151], v[222:225], v[116:119]
	v_mfma_f32_16x16x32_bf16 v[112:115], v[156:159], v[222:225], v[112:115]
	v_mfma_f32_16x16x32_bf16 v[100:103], v[148:151], v[230:233], v[100:103]
	v_mfma_f32_16x16x32_bf16 v[96:99], v[156:159], v[230:233], v[96:99]
	v_mfma_f32_16x16x32_bf16 v[84:87], v[148:151], v[238:241], v[84:87]
	v_mfma_f32_16x16x32_bf16 v[80:83], v[156:159], v[238:241], v[80:83]
	s_barrier
	s_add_i32 s82, s82, s38
	v_lshl_add_u64 v[200:201], vcc, 0, v[164:165]
	s_mov_b32 m0, s82
	ds_read_b128 v[188:191], v218 offset:16384
	ds_read_b128 v[192:195], v218 offset:17408
	ds_read_b128 v[196:199], v218 offset:18432
	ds_read_b128 v[222:225], v218 offset:19456
	ds_read_b128 v[226:229], v218 offset:20480
	ds_read_b128 v[230:233], v218 offset:21504
	ds_read_b128 v[234:237], v218 offset:22528
	ds_read_b128 v[238:241], v218 offset:23552
	global_load_lds_dwordx4 v[200:201], off
	s_add_i32 m0, s82, 0x2000
	v_lshl_add_u64 v[242:243], vcc, 0, v[160:161]
	s_add_u32 vcc_lo, vcc_lo, s90
	s_addc_u32 vcc_hi, vcc_hi, 0
	s_add_i32 s82, s85, s38
	global_load_lds_dwordx4 v[242:243], off
	v_lshl_add_u64 v[244:245], vcc, 0, v[164:165]
	s_mov_b32 m0, s82
	v_lshl_add_u64 v[246:247], vcc, 0, v[160:161]
	global_load_lds_dwordx4 v[244:245], off
	s_add_i32 m0, s82, 0x2000
	v_lshl_add_u64 v[248:249], s[54:55], 0, v[164:165]
	global_load_lds_dwordx4 v[246:247], off
	s_mov_b32 m0, s45
	v_lshl_add_u64 v[250:251], s[54:55], 0, v[160:161]
	global_load_lds_dwordx4 v[248:249], off
	s_mov_b32 m0, s48
	s_nop 0
	global_load_lds_dwordx4 v[250:251], off
	s_waitcnt vmcnt(8)
	s_waitcnt lgkmcnt(0)
	s_barrier
	v_mfma_f32_16x16x32_bf16 v[76:79], v[32:35], v[188:191], v[76:79]
	v_mfma_f32_16x16x32_bf16 v[72:75], v[48:51], v[188:191], v[72:75]
	v_mfma_f32_16x16x32_bf16 v[60:63], v[32:35], v[196:199], v[60:63]
	v_mfma_f32_16x16x32_bf16 v[56:59], v[48:51], v[196:199], v[56:59]
	v_mfma_f32_16x16x32_bf16 v[28:31], v[32:35], v[226:229], v[28:31]
	v_mfma_f32_16x16x32_bf16 v[24:27], v[48:51], v[226:229], v[24:27]
	v_mfma_f32_16x16x32_bf16 v[12:15], v[32:35], v[234:237], v[12:15]
	v_mfma_f32_16x16x32_bf16 v[8:11], v[48:51], v[234:237], v[8:11]
	v_mfma_f32_16x16x32_bf16 v[76:79], v[36:39], v[192:195], v[76:79]
	v_mfma_f32_16x16x32_bf16 v[72:75], v[52:55], v[192:195], v[72:75]
	v_mfma_f32_16x16x32_bf16 v[60:63], v[36:39], v[222:225], v[60:63]
	v_mfma_f32_16x16x32_bf16 v[56:59], v[52:55], v[222:225], v[56:59]
	v_mfma_f32_16x16x32_bf16 v[28:31], v[36:39], v[230:233], v[28:31]
	v_mfma_f32_16x16x32_bf16 v[24:27], v[52:55], v[230:233], v[24:27]
	v_mfma_f32_16x16x32_bf16 v[12:15], v[36:39], v[238:241], v[12:15]
	v_mfma_f32_16x16x32_bf16 v[8:11], v[52:55], v[238:241], v[8:11]
	v_mfma_f32_16x16x32_bf16 v[44:47], v[144:147], v[196:199], v[44:47]
	v_mfma_f32_16x16x32_bf16 v[40:43], v[152:155], v[196:199], v[40:43]
	v_mfma_f32_16x16x32_bf16 v[20:23], v[144:147], v[226:229], v[20:23]
	v_mfma_f32_16x16x32_bf16 v[16:19], v[152:155], v[226:229], v[16:19]
	v_mfma_f32_16x16x32_bf16 v[4:7], v[144:147], v[234:237], v[4:7]
	v_mfma_f32_16x16x32_bf16 v[0:3], v[152:155], v[234:237], v[0:3]
	v_mfma_f32_16x16x32_bf16 v[32:35], v[144:147], v[188:191], v[68:71]
	v_mfma_f32_16x16x32_bf16 v[36:39], v[152:155], v[188:191], v[64:67]
	v_mfma_f32_16x16x32_bf16 v[44:47], v[148:151], v[222:225], v[44:47]
	v_mfma_f32_16x16x32_bf16 v[40:43], v[156:159], v[222:225], v[40:43]
	v_mfma_f32_16x16x32_bf16 v[20:23], v[148:151], v[230:233], v[20:23]
	v_mfma_f32_16x16x32_bf16 v[16:19], v[156:159], v[230:233], v[16:19]
	v_mfma_f32_16x16x32_bf16 v[4:7], v[148:151], v[238:241], v[4:7]
	v_mfma_f32_16x16x32_bf16 v[0:3], v[156:159], v[238:241], v[0:3]
	v_mfma_f32_16x16x32_bf16 v[32:35], v[148:151], v[192:195], v[32:35]
	v_mfma_f32_16x16x32_bf16 v[36:39], v[156:159], v[192:195], v[36:39]
	s_barrier
; #define PG8_STAGE(bufoff, gbase, voff) do { _Pragma("unroll") for (int _i = 0; _i < 2; ++_i) \
;         __builtin_amdgcn_global_load_lds((const unsigned*)((const char*)(gbase) + (voff)[_i]), (PG8_LAS unsigned*)(lds + (bufoff) + ldsw + _i * 8192), 16, 0, 0); } while (0)
; #define PG8_LDA(dst, b, h) do { _Pragma("unroll") for (int m = 0; m < 4; ++m) _Pragma("unroll") for (int k = 0; k < 2; ++k) dst[m][k] = *(const PG8_LAS bf16x8*)(lds + PG8_SA(b, h) + aoff + m * 2048 + k * 1024); } while (0)
; #define PG8_LDB(dst, b, h) do { _Pragma("unroll") for (int n = 0; n < 2; ++n) _Pragma("unroll") for (int k = 0; k < 2; ++k) dst[n][k] = *(const PG8_LAS bf16x8*)(lds + PG8_SB(b, h) + boff + n * 2048 + k * 1024); } while (0)
; #define PG8_MMA(ai, bj, At, Bt) do { __builtin_amdgcn_s_setprio(1); _Pragma("unroll") for (int m = 0; m < 4; ++m) _Pragma("unroll") for (int n = 0; n < 2; ++n) _Pragma("unroll") for (int k = 0; k < 2; ++k) \
;         acc[ai][bj][m][n] = __builtin_amdgcn_mfma_f32_16x16x32_bf16(Bt[n][k], At[m][k], acc[ai][bj][m][n], 0, 0, 0); __builtin_amdgcn_s_setprio(0); } while (0)
; #define PG8_WAIT_V(n) asm volatile("s_waitcnt vmcnt(" #n ")" ::: "memory")
; #define PG8_WAIT_L(n) asm volatile("s_waitcnt lgkmcnt(" #n ")" ::: "memory")
; #define PG8_BAR __builtin_amdgcn_s_barrier()
; #define PG8_SCHED __builtin_amdgcn_sched_barrier(0)
; template <class Epi, class Sched, bool ALIGN_EPI = false, bool SP2 = false>
; __device__ __forceinline__ void gemm_phase(PG8_LAS unsigned char* lds, const Gemm g, const Sched& S, const Epi& E, const int tid) {
;     ...
;             PG8_LDB(B0, 1, 0); PG8_LDB(B1, 1, 1); PG8_SCHED; PG8_LDA(At, 1, 0); PG8_STAGE(PG8_SA(0, 1), a2 + hstep, voffA);
;             PG8_WAIT_V(8); PG8_WAIT_L(0); PG8_BAR; PG8_MMA(0, 0, At, B0); PG8_MMA(0, 1, At, B1); PG8_BAR; PG8_SCHED;
;             PG8_LDA(At, 1, 1); PG8_STAGE(PG8_SB(1, 0), b3, voffB); PG8_STAGE(PG8_SB(1, 1), b3 + hstep, voffB); PG8_STAGE(PG8_SA(1, 0), a3, voffA);
;             PG8_WAIT_V(8); PG8_WAIT_L(0); PG8_BAR; PG8_MMA(1, 0, At, B0); PG8_MMA(1, 1, At, B1); PG8_BAR; PG8_SCHED;
;     ...
;         if constexpr (ALIGN_EPI) { if (wr == 0) PG8_BAR; }
.Lres_mid:
	s_add_i32 s82, 0, 0x18000
	s_add_i32 s85, 0, 0x1c000
	v_add_u32_e32 v68, s82, v181
	v_add_u32_e32 v156, s85, v181
	ds_read_b128 v[48:51], v68
	ds_read_b128 v[52:55], v68 offset:1024
	ds_read_b128 v[64:67], v68 offset:2048
	ds_read_b128 v[68:71], v68 offset:3072
	ds_read_b128 v[144:147], v156
	ds_read_b128 v[148:151], v156 offset:1024
	ds_read_b128 v[152:155], v156 offset:2048
	ds_read_b128 v[156:159], v156 offset:3072
	s_add_u32 s54, s54, s90
	s_addc_u32 s55, s55, 0
	s_mov_b32 m0, s49
	v_lshl_add_u64 v[166:167], s[54:55], 0, v[164:165]
	ds_read_b128 v[188:191], v218 offset:32768
	ds_read_b128 v[192:195], v218 offset:33792
	ds_read_b128 v[196:199], v218 offset:34816
	ds_read_b128 v[222:225], v218 offset:35840
	ds_read_b128 v[226:229], v218 offset:36864
	ds_read_b128 v[230:233], v218 offset:37888
	ds_read_b128 v[234:237], v218 offset:38912
	ds_read_b128 v[238:241], v218 offset:39936
	global_load_lds_dwordx4 v[166:167], off
	v_lshl_add_u64 v[166:167], s[54:55], 0, v[160:161]
	s_mov_b32 m0, s50
	s_nop 0
	global_load_lds_dwordx4 v[166:167], off
	s_waitcnt vmcnt(8)
	s_waitcnt lgkmcnt(0)
	s_barrier
	v_mfma_f32_16x16x32_bf16 v[140:143], v[48:51], v[188:191], v[140:143]
	v_mfma_f32_16x16x32_bf16 v[136:139], v[64:67], v[188:191], v[136:139]
	v_mfma_f32_16x16x32_bf16 v[124:127], v[48:51], v[196:199], v[124:127]
	v_mfma_f32_16x16x32_bf16 v[120:123], v[64:67], v[196:199], v[120:123]
	v_mfma_f32_16x16x32_bf16 v[108:111], v[48:51], v[226:229], v[108:111]
	v_mfma_f32_16x16x32_bf16 v[104:107], v[64:67], v[226:229], v[104:107]
	v_mfma_f32_16x16x32_bf16 v[92:95], v[48:51], v[234:237], v[92:95]
	v_mfma_f32_16x16x32_bf16 v[88:91], v[64:67], v[234:237], v[88:91]
	v_mfma_f32_16x16x32_bf16 v[140:143], v[52:55], v[192:195], v[140:143]
	v_mfma_f32_16x16x32_bf16 v[136:139], v[68:71], v[192:195], v[136:139]
	v_mfma_f32_16x16x32_bf16 v[124:127], v[52:55], v[222:225], v[124:127]
	v_mfma_f32_16x16x32_bf16 v[120:123], v[68:71], v[222:225], v[120:123]
	v_mfma_f32_16x16x32_bf16 v[108:111], v[52:55], v[230:233], v[108:111]
	v_mfma_f32_16x16x32_bf16 v[104:107], v[68:71], v[230:233], v[104:107]
	v_mfma_f32_16x16x32_bf16 v[92:95], v[52:55], v[238:241], v[92:95]
	v_mfma_f32_16x16x32_bf16 v[88:91], v[68:71], v[238:241], v[88:91]
	v_mfma_f32_16x16x32_bf16 v[132:135], v[144:147], v[188:191], v[132:135]
	v_mfma_f32_16x16x32_bf16 v[128:131], v[152:155], v[188:191], v[128:131]
	v_mfma_f32_16x16x32_bf16 v[116:119], v[144:147], v[196:199], v[116:119]
	v_mfma_f32_16x16x32_bf16 v[112:115], v[152:155], v[196:199], v[112:115]
	v_mfma_f32_16x16x32_bf16 v[100:103], v[144:147], v[226:229], v[100:103]
	v_mfma_f32_16x16x32_bf16 v[96:99], v[152:155], v[226:229], v[96:99]
	v_mfma_f32_16x16x32_bf16 v[84:87], v[144:147], v[234:237], v[84:87]
	v_mfma_f32_16x16x32_bf16 v[80:83], v[152:155], v[234:237], v[80:83]
	v_mfma_f32_16x16x32_bf16 v[132:135], v[148:151], v[192:195], v[132:135]
	v_mfma_f32_16x16x32_bf16 v[128:131], v[156:159], v[192:195], v[128:131]
	v_mfma_f32_16x16x32_bf16 v[116:119], v[148:151], v[222:225], v[116:119]
	v_mfma_f32_16x16x32_bf16 v[112:115], v[156:159], v[222:225], v[112:115]
	v_mfma_f32_16x16x32_bf16 v[100:103], v[148:151], v[230:233], v[100:103]
	v_mfma_f32_16x16x32_bf16 v[96:99], v[156:159], v[230:233], v[96:99]
	v_mfma_f32_16x16x32_bf16 v[84:87], v[148:151], v[238:241], v[84:87]
	v_mfma_f32_16x16x32_bf16 v[80:83], v[156:159], v[238:241], v[80:83]
	s_barrier
	s_add_i32 s54, s82, s38
	v_lshl_add_u64 v[166:167], v[200:201], 0, s[86:87]
	s_mov_b32 m0, s54
	ds_read_b128 v[188:191], v218 offset:49152
	ds_read_b128 v[192:195], v218 offset:50176
	ds_read_b128 v[196:199], v218 offset:51200
	ds_read_b128 v[222:225], v218 offset:52224
	ds_read_b128 v[226:229], v218 offset:53248
	ds_read_b128 v[230:233], v218 offset:54272
	ds_read_b128 v[234:237], v218 offset:55296
	ds_read_b128 v[238:241], v218 offset:56320
	global_load_lds_dwordx4 v[166:167], off
	v_lshl_add_u64 v[166:167], v[242:243], 0, s[86:87]
	s_add_i32 m0, s54, 0x2000
	s_add_i32 s54, s85, s38
	global_load_lds_dwordx4 v[166:167], off
	v_lshl_add_u64 v[166:167], v[244:245], 0, s[86:87]
	s_mov_b32 m0, s54
	s_nop 0
	global_load_lds_dwordx4 v[166:167], off
	v_lshl_add_u64 v[166:167], v[246:247], 0, s[86:87]
	s_add_i32 m0, s54, 0x2000
	s_nop 0
	global_load_lds_dwordx4 v[166:167], off
	v_lshl_add_u64 v[166:167], v[248:249], 0, s[86:87]
	s_mov_b32 m0, s57
	s_nop 0
	global_load_lds_dwordx4 v[166:167], off
	v_lshl_add_u64 v[166:167], v[250:251], 0, s[86:87]
	s_mov_b32 m0, s58
	s_nop 0
	global_load_lds_dwordx4 v[166:167], off
	s_waitcnt vmcnt(8)
	s_waitcnt lgkmcnt(0)
	s_barrier
	v_mfma_f32_16x16x32_bf16 v[76:79], v[48:51], v[188:191], v[76:79]
	v_mfma_f32_16x16x32_bf16 v[72:75], v[64:67], v[188:191], v[72:75]
	v_mfma_f32_16x16x32_bf16 v[60:63], v[48:51], v[196:199], v[60:63]
	v_mfma_f32_16x16x32_bf16 v[56:59], v[64:67], v[196:199], v[56:59]
	v_mfma_f32_16x16x32_bf16 v[28:31], v[48:51], v[226:229], v[28:31]
	v_mfma_f32_16x16x32_bf16 v[24:27], v[64:67], v[226:229], v[24:27]
	v_mfma_f32_16x16x32_bf16 v[12:15], v[48:51], v[234:237], v[12:15]
	v_mfma_f32_16x16x32_bf16 v[8:11], v[64:67], v[234:237], v[8:11]
	v_mfma_f32_16x16x32_bf16 v[76:79], v[52:55], v[192:195], v[76:79]
	v_mfma_f32_16x16x32_bf16 v[72:75], v[68:71], v[192:195], v[72:75]
	v_mfma_f32_16x16x32_bf16 v[60:63], v[52:55], v[222:225], v[60:63]
	v_mfma_f32_16x16x32_bf16 v[56:59], v[68:71], v[222:225], v[56:59]
	v_mfma_f32_16x16x32_bf16 v[28:31], v[52:55], v[230:233], v[28:31]
	v_mfma_f32_16x16x32_bf16 v[24:27], v[68:71], v[230:233], v[24:27]
	v_mfma_f32_16x16x32_bf16 v[12:15], v[52:55], v[238:241], v[12:15]
	v_mfma_f32_16x16x32_bf16 v[8:11], v[68:71], v[238:241], v[8:11]
	v_mfma_f32_16x16x32_bf16 v[32:35], v[144:147], v[188:191], v[32:35]
	v_mfma_f32_16x16x32_bf16 v[68:71], v[148:151], v[192:195], v[32:35]
	v_mfma_f32_16x16x32_bf16 v[32:35], v[152:155], v[188:191], v[36:39]
	v_mfma_f32_16x16x32_bf16 v[64:67], v[156:159], v[192:195], v[32:35]
	v_mfma_f32_16x16x32_bf16 v[32:35], v[144:147], v[196:199], v[44:47]
	v_mfma_f32_16x16x32_bf16 v[44:47], v[148:151], v[222:225], v[32:35]
	v_mfma_f32_16x16x32_bf16 v[32:35], v[152:155], v[196:199], v[40:43]
	v_mfma_f32_16x16x32_bf16 v[20:23], v[144:147], v[226:229], v[20:23]
	v_mfma_f32_16x16x32_bf16 v[16:19], v[152:155], v[226:229], v[16:19]
	v_mfma_f32_16x16x32_bf16 v[4:7], v[144:147], v[234:237], v[4:7]
	v_mfma_f32_16x16x32_bf16 v[0:3], v[152:155], v[234:237], v[0:3]
	v_mfma_f32_16x16x32_bf16 v[40:43], v[156:159], v[222:225], v[32:35]
	v_mfma_f32_16x16x32_bf16 v[20:23], v[148:151], v[230:233], v[20:23]
	v_mfma_f32_16x16x32_bf16 v[16:19], v[156:159], v[230:233], v[16:19]
	v_mfma_f32_16x16x32_bf16 v[4:7], v[148:151], v[238:241], v[4:7]
	v_mfma_f32_16x16x32_bf16 v[0:3], v[156:159], v[238:241], v[0:3]
	s_barrier
	s_add_u32 s73, s73, 0x100
	s_addc_u32 s81, s81, 0
	s_add_u32 s8, s8, 0x100
	s_addc_u32 s9, s9, 0
	s_cmp_ge_u32 s84, s60
	s_mov_b32 s54, s84
	s_cbranch_scc0 .LBB0_1305
	s_and_b64 vcc, exec, s[18:19]
	s_cbranch_vccz .LBB0_1308
	s_barrier

; #define PG8_STAGE(bufoff, gbase, voff) do { _Pragma("unroll") for (int _i = 0; _i < 2; ++_i) \
;         __builtin_amdgcn_global_load_lds((const unsigned*)((const char*)(gbase) + (voff)[_i]), (PG8_LAS unsigned*)(lds + (bufoff) + ldsw + _i * 8192), 16, 0, 0); } while (0)
; #define PG8_LDA(dst, b, h) do { _Pragma("unroll") for (int m = 0; m < 4; ++m) _Pragma("unroll") for (int k = 0; k < 2; ++k) dst[m][k] = *(const PG8_LAS bf16x8*)(lds + PG8_SA(b, h) + aoff + m * 2048 + k * 1024); } while (0)
; #define PG8_LDB(dst, b, h) do { _Pragma("unroll") for (int n = 0; n < 2; ++n) _Pragma("unroll") for (int k = 0; k < 2; ++k) dst[n][k] = *(const PG8_LAS bf16x8*)(lds + PG8_SB(b, h) + boff + n * 2048 + k * 1024); } while (0)
; #define PG8_WAIT_V(n) asm volatile("s_waitcnt vmcnt(" #n ")" ::: "memory")
; #define PG8_WAIT_L(n) asm volatile("s_waitcnt lgkmcnt(" #n ")" ::: "memory")
; #define PG8_BAR __builtin_amdgcn_s_barrier()
; #define PG8_SCHED __builtin_amdgcn_sched_barrier(0)
; template <class Epi, class Sched, bool ALIGN_EPI = false, bool SP2 = false>
; __device__ __forceinline__ void gemm_phase(PG8_LAS unsigned char* lds, const Gemm g, const Sched& S, const Epi& E, const int tid) {
;     ...
;         const bool has_next = S.next(ui + 1, nxt);
;         const char* nA = has_next ? (const char*)g.A + (size_t)nxt.pm * tstep : cA; const char* nB = has_next ? (const char*)g.Bt + (size_t)nxt.pn * tstep : cB;
;         for (int t = 0; t < nt; t += 2) {
;             const bool last = (t == nt - 2);
;             const char* a1 = cA + (size_t)(t + 1) * kstep;
;             const char* a2 = last ? nA : cA + (size_t)(t + 2) * kstep; const char* b2 = last ? nB : cB + (size_t)(t + 2) * kstep;
;             const char* a3 = a2 + kstep; const char* b3 = b2 + kstep;
;             if (last && has_next) S.a_ready(nxt);
;             if constexpr (SP2) {
;             PG8_LDB(B0, 0, 0); PG8_LDB(B1, 0, 1); PG8_SCHED; PG8_LDA(At, 0, 0); PG8_STAGE(PG8_SA(1, 1), a1 + hstep, voffA);
;             PG8_WAIT_V(8); PG8_WAIT_L(0); PG8_BAR; PG8_MMA(0, 0, At, B0); PG8_MMA(0, 1, At, B1); PG8_BAR; PG8_SCHED;
;             PG8_LDA(At, 0, 1); PG8_STAGE(PG8_SB(0, 0), b2, voffB); PG8_STAGE(PG8_SB(0, 1), b2 + hstep, voffB); PG8_STAGE(PG8_SA(0, 0), a2, voffA);
;             PG8_WAIT_V(8); PG8_WAIT_L(0); PG8_BAR; PG8_MMA(1, 0, At, B0); PG8_MMA(1, 1, At, B1); PG8_BAR; PG8_SCHED;
.LBB0_1491:
	s_ashr_i32 s11, s10, 31
	s_lshl_b64 s[12:13], s[10:11], 19
	s_add_u32 s12, s88, s12
	s_addc_u32 s13, s89, s13
	s_and_b64 s[14:15], s[4:5], exec
	s_cselect_b32 s11, s13, s21
	s_cselect_b32 s55, s12, s20
	s_ashr_i32 s9, s8, 31
	s_lshl_b64 s[14:15], s[8:9], 19
	s_add_u32 s14, s37, s14
	s_addc_u32 s15, s38, s15
	s_and_b64 s[52:53], s[4:5], exec
	s_cselect_b32 s9, s15, s19
	s_cselect_b32 s56, s14, s18
	s_add_u32 s57, s18, 0x100
	s_addc_u32 s58, s19, 0
	s_add_u32 s18, s20, 0x40080
	s_addc_u32 s19, s21, 0
	s_mov_b32 s59, -2
	s_add_u32 s20, s18, 0xfffc0080
	s_addc_u32 s21, s19, -1
	s_add_i32 s60, 0, 0x10000
	s_cmp_eq_u32 s59, 12
	s_cselect_b32 s53, s11, s21
	s_cselect_b32 s52, s55, s20
	s_cselect_b32 s21, s9, s58
	s_cselect_b32 s20, s56, s57
	s_add_i32 s62, 0, 0x14000
	v_add_u32_e32 v154, s60, v143
	v_add_u32_e32 v162, s62, v143
	ds_read_b128 v[138:141], v154
	ds_read_b128 v[146:149], v154 offset:1024
	ds_read_b128 v[150:153], v154 offset:2048
	ds_read_b128 v[154:157], v154 offset:3072
	ds_read_b128 v[158:161], v162
	ds_read_b128 v[180:183], v162 offset:1024
	ds_read_b128 v[184:187], v162 offset:2048
	ds_read_b128 v[188:191], v162 offset:3072
	v_lshl_add_u64 v[162:163], s[18:19], 0, v[136:137]
	s_add_i32 m0, s43, 0xc000
	ds_read_b128 v[192:195], v145
	ds_read_b128 v[196:199], v145 offset:1024
	ds_read_b128 v[214:217], v145 offset:2048
	ds_read_b128 v[218:221], v145 offset:3072
	ds_read_b128 v[222:225], v145 offset:4096
	ds_read_b128 v[226:229], v145 offset:5120
	ds_read_b128 v[230:233], v145 offset:6144
	ds_read_b128 v[234:237], v145 offset:7168
	global_load_lds_dwordx4 v[162:163], off
	v_lshl_add_u64 v[162:163], s[18:19], 0, v[134:135]
	s_add_i32 m0, s43, 0xe000
	s_nop 0
	global_load_lds_dwordx4 v[162:163], off
	s_waitcnt vmcnt(8)
	s_waitcnt lgkmcnt(0)
	s_barrier
	v_mfma_f32_16x16x32_bf16 v[124:127], v[138:141], v[192:195], 0
	v_mfma_f32_16x16x32_bf16 v[116:119], v[150:153], v[192:195], 0
	v_mfma_f32_16x16x32_bf16 v[108:111], v[138:141], v[214:217], 0
	v_mfma_f32_16x16x32_bf16 v[100:103], v[150:153], v[214:217], 0
	v_mfma_f32_16x16x32_bf16 v[92:95], v[138:141], v[222:225], 0
	v_mfma_f32_16x16x32_bf16 v[84:87], v[150:153], v[222:225], 0
	v_mfma_f32_16x16x32_bf16 v[76:79], v[138:141], v[230:233], 0
	v_mfma_f32_16x16x32_bf16 v[68:71], v[150:153], v[230:233], 0
	v_mfma_f32_16x16x32_bf16 v[124:127], v[146:149], v[196:199], v[124:127]
	v_mfma_f32_16x16x32_bf16 v[116:119], v[154:157], v[196:199], v[116:119]
	v_mfma_f32_16x16x32_bf16 v[108:111], v[146:149], v[218:221], v[108:111]
	v_mfma_f32_16x16x32_bf16 v[100:103], v[154:157], v[218:221], v[100:103]
	v_mfma_f32_16x16x32_bf16 v[92:95], v[146:149], v[226:229], v[92:95]
	v_mfma_f32_16x16x32_bf16 v[84:87], v[154:157], v[226:229], v[84:87]
	v_mfma_f32_16x16x32_bf16 v[76:79], v[146:149], v[234:237], v[76:79]
	v_mfma_f32_16x16x32_bf16 v[68:71], v[154:157], v[234:237], v[68:71]
	v_mfma_f32_16x16x32_bf16 v[120:123], v[158:161], v[192:195], 0
	v_mfma_f32_16x16x32_bf16 v[112:115], v[184:187], v[192:195], 0
	v_mfma_f32_16x16x32_bf16 v[104:107], v[158:161], v[214:217], 0
	v_mfma_f32_16x16x32_bf16 v[96:99], v[184:187], v[214:217], 0
	v_mfma_f32_16x16x32_bf16 v[88:91], v[158:161], v[222:225], 0
	v_mfma_f32_16x16x32_bf16 v[80:83], v[184:187], v[222:225], 0
	v_mfma_f32_16x16x32_bf16 v[72:75], v[158:161], v[230:233], 0
	v_mfma_f32_16x16x32_bf16 v[64:67], v[184:187], v[230:233], 0
	v_mfma_f32_16x16x32_bf16 v[120:123], v[180:183], v[196:199], v[120:123]
	v_mfma_f32_16x16x32_bf16 v[112:115], v[188:191], v[196:199], v[112:115]
	v_mfma_f32_16x16x32_bf16 v[104:107], v[180:183], v[218:221], v[104:107]
	v_mfma_f32_16x16x32_bf16 v[96:99], v[188:191], v[218:221], v[96:99]
	v_mfma_f32_16x16x32_bf16 v[88:91], v[180:183], v[226:229], v[88:91]
	v_mfma_f32_16x16x32_bf16 v[80:83], v[188:191], v[226:229], v[80:83]
	v_mfma_f32_16x16x32_bf16 v[72:75], v[180:183], v[234:237], v[72:75]
	v_mfma_f32_16x16x32_bf16 v[64:67], v[188:191], v[234:237], v[64:67]
	s_barrier
	s_add_i32 s60, s60, s41
	v_lshl_add_u64 v[162:163], s[20:21], 0, v[164:165]
	s_mov_b32 m0, s60
	ds_read_b128 v[192:195], v145 offset:16384
	ds_read_b128 v[196:199], v145 offset:17408
	ds_read_b128 v[214:217], v145 offset:18432
	ds_read_b128 v[218:221], v145 offset:19456
	ds_read_b128 v[222:225], v145 offset:20480
	ds_read_b128 v[226:229], v145 offset:21504
	ds_read_b128 v[230:233], v145 offset:22528
	ds_read_b128 v[234:237], v145 offset:23552
	global_load_lds_dwordx4 v[162:163], off
	s_add_i32 m0, s60, 0x2000
	s_add_u32 s60, s20, 0x40000
	v_lshl_add_u64 v[200:201], s[20:21], 0, v[128:129]
	s_addc_u32 s61, s21, 0
	s_add_i32 s62, s62, s41
	global_load_lds_dwordx4 v[200:201], off
	v_lshl_add_u64 v[238:239], s[60:61], 0, v[164:165]
	s_mov_b32 m0, s62
	v_lshl_add_u64 v[240:241], s[52:53], 0, v[130:131]
	global_load_lds_dwordx4 v[238:239], off
	v_lshl_add_u64 v[238:239], s[60:61], 0, v[128:129]
	s_add_i32 m0, s62, 0x2000
	s_nop 0
	global_load_lds_dwordx4 v[238:239], off
	v_lshl_add_u64 v[238:239], s[52:53], 0, v[132:133]
	s_mov_b32 m0, s43
	s_nop 0
	global_load_lds_dwordx4 v[238:239], off
	s_mov_b32 m0, s44
	s_nop 0
	global_load_lds_dwordx4 v[240:241], off
	s_waitcnt vmcnt(8)
	s_waitcnt lgkmcnt(0)
	s_barrier
; #define PG8_STAGE(bufoff, gbase, voff) do { _Pragma("unroll") for (int _i = 0; _i < 2; ++_i) \
;         __builtin_amdgcn_global_load_lds((const unsigned*)((const char*)(gbase) + (voff)[_i]), (PG8_LAS unsigned*)(lds + (bufoff) + ldsw + _i * 8192), 16, 0, 0); } while (0)
; #define PG8_LDA(dst, b, h) do { _Pragma("unroll") for (int m = 0; m < 4; ++m) _Pragma("unroll") for (int k = 0; k < 2; ++k) dst[m][k] = *(const PG8_LAS bf16x8*)(lds + PG8_SA(b, h) + aoff + m * 2048 + k * 1024); } while (0)
; #define PG8_LDB(dst, b, h) do { _Pragma("unroll") for (int n = 0; n < 2; ++n) _Pragma("unroll") for (int k = 0; k < 2; ++k) dst[n][k] = *(const PG8_LAS bf16x8*)(lds + PG8_SB(b, h) + boff + n * 2048 + k * 1024); } while (0)
; #define PG8_MMA(ai, bj, At, Bt) do { __builtin_amdgcn_s_setprio(1); _Pragma("unroll") for (int m = 0; m < 4; ++m) _Pragma("unroll") for (int n = 0; n < 2; ++n) _Pragma("unroll") for (int k = 0; k < 2; ++k) \
;         acc[ai][bj][m][n] = __builtin_amdgcn_mfma_f32_16x16x32_bf16(Bt[n][k], At[m][k], acc[ai][bj][m][n], 0, 0, 0); __builtin_amdgcn_s_setprio(0); } while (0)
; #define PG8_WAIT_V(n) asm volatile("s_waitcnt vmcnt(" #n ")" ::: "memory")
; #define PG8_BAR __builtin_amdgcn_s_barrier()
; template <class Epi, class Sched, bool ALIGN_EPI = false, bool SP2 = false>
; __device__ __forceinline__ void gemm_phase(PG8_LAS unsigned char* lds, const Gemm g, const Sched& S, const Epi& E, const int tid) {
;     ...
;         for (int t = 0; t < nt; t += 2) {
;             const bool last = (t == nt - 2);
;             const char* a1 = cA + (size_t)(t + 1) * kstep;
;             const char* a2 = last ? nA : cA + (size_t)(t + 2) * kstep; const char* b2 = last ? nB : cB + (size_t)(t + 2) * kstep;
;             const char* a3 = a2 + kstep; const char* b3 = b2 + kstep;
;             if (last && has_next) S.a_ready(nxt);
;             if constexpr (SP2) {
;             PG8_LDB(B0, 0, 0); PG8_LDB(B1, 0, 1); PG8_SCHED; PG8_LDA(At, 0, 0); PG8_STAGE(PG8_SA(1, 1), a1 + hstep, voffA);
;             PG8_WAIT_V(8); PG8_WAIT_L(0); PG8_BAR; PG8_MMA(0, 0, At, B0); PG8_MMA(0, 1, At, B1); PG8_BAR; PG8_SCHED;
;             PG8_LDA(At, 0, 1); PG8_STAGE(PG8_SB(0, 0), b2, voffB); PG8_STAGE(PG8_SB(0, 1), b2 + hstep, voffB); PG8_STAGE(PG8_SA(0, 0), a2, voffA);
;             PG8_WAIT_V(8); PG8_WAIT_L(0); PG8_BAR; PG8_MMA(1, 0, At, B0); PG8_MMA(1, 1, At, B1); PG8_BAR; PG8_SCHED;
	v_mfma_f32_16x16x32_bf16 v[60:63], v[138:141], v[192:195], 0
	v_mfma_f32_16x16x32_bf16 v[52:55], v[150:153], v[192:195], 0
	v_mfma_f32_16x16x32_bf16 v[44:47], v[138:141], v[214:217], 0
	v_mfma_f32_16x16x32_bf16 v[36:39], v[150:153], v[214:217], 0
	v_mfma_f32_16x16x32_bf16 v[28:31], v[138:141], v[222:225], 0
	v_mfma_f32_16x16x32_bf16 v[20:23], v[150:153], v[222:225], 0
	v_mfma_f32_16x16x32_bf16 v[12:15], v[138:141], v[230:233], 0
	v_mfma_f32_16x16x32_bf16 v[4:7], v[150:153], v[230:233], 0
	v_mfma_f32_16x16x32_bf16 v[60:63], v[146:149], v[196:199], v[60:63]
	v_mfma_f32_16x16x32_bf16 v[52:55], v[154:157], v[196:199], v[52:55]
	v_mfma_f32_16x16x32_bf16 v[44:47], v[146:149], v[218:221], v[44:47]
	v_mfma_f32_16x16x32_bf16 v[36:39], v[154:157], v[218:221], v[36:39]
	v_mfma_f32_16x16x32_bf16 v[28:31], v[146:149], v[226:229], v[28:31]
	v_mfma_f32_16x16x32_bf16 v[20:23], v[154:157], v[226:229], v[20:23]
	v_mfma_f32_16x16x32_bf16 v[12:15], v[146:149], v[234:237], v[12:15]
	v_mfma_f32_16x16x32_bf16 v[4:7], v[154:157], v[234:237], v[4:7]
	v_mfma_f32_16x16x32_bf16 v[56:59], v[158:161], v[192:195], 0
	v_mfma_f32_16x16x32_bf16 v[48:51], v[184:187], v[192:195], 0
	v_mfma_f32_16x16x32_bf16 v[40:43], v[158:161], v[214:217], 0
	v_mfma_f32_16x16x32_bf16 v[32:35], v[184:187], v[214:217], 0
	v_mfma_f32_16x16x32_bf16 v[24:27], v[158:161], v[222:225], 0
	v_mfma_f32_16x16x32_bf16 v[16:19], v[184:187], v[222:225], 0
	v_mfma_f32_16x16x32_bf16 v[8:11], v[158:161], v[230:233], 0
	v_mfma_f32_16x16x32_bf16 v[0:3], v[184:187], v[230:233], 0
	v_mfma_f32_16x16x32_bf16 v[56:59], v[180:183], v[196:199], v[56:59]
	v_mfma_f32_16x16x32_bf16 v[48:51], v[188:191], v[196:199], v[48:51]
	v_mfma_f32_16x16x32_bf16 v[40:43], v[180:183], v[218:221], v[40:43]
	v_mfma_f32_16x16x32_bf16 v[32:35], v[188:191], v[218:221], v[32:35]
	v_mfma_f32_16x16x32_bf16 v[24:27], v[180:183], v[226:229], v[24:27]
	v_mfma_f32_16x16x32_bf16 v[16:19], v[188:191], v[226:229], v[16:19]
	v_mfma_f32_16x16x32_bf16 v[8:11], v[180:183], v[234:237], v[8:11]
	v_mfma_f32_16x16x32_bf16 v[0:3], v[188:191], v[234:237], v[0:3]
	s_barrier
	s_branch .Lsw_mid
.LBB0_1492:
	s_add_u32 s20, s18, 0xfffc0080
	s_addc_u32 s21, s19, -1
	s_add_i32 s60, 0, 0x10000
	s_cmp_eq_u32 s59, 12
	s_cselect_b32 s53, s11, s21
	s_cselect_b32 s52, s55, s20
	s_cselect_b32 s21, s9, s58
	s_cselect_b32 s20, s56, s57
	s_add_i32 s62, 0, 0x14000
	v_add_u32_e32 v154, s60, v143
	v_add_u32_e32 v162, s62, v143
	ds_read_b128 v[138:141], v154
	ds_read_b128 v[146:149], v154 offset:1024
	ds_read_b128 v[150:153], v154 offset:2048
	ds_read_b128 v[154:157], v154 offset:3072
	ds_read_b128 v[158:161], v162
	ds_read_b128 v[180:183], v162 offset:1024
	ds_read_b128 v[184:187], v162 offset:2048
	ds_read_b128 v[188:191], v162 offset:3072
	v_lshl_add_u64 v[162:163], s[18:19], 0, v[136:137]
	s_add_i32 m0, s43, 0xc000
	ds_read_b128 v[192:195], v145
	ds_read_b128 v[196:199], v145 offset:1024
	ds_read_b128 v[214:217], v145 offset:2048
	ds_read_b128 v[218:221], v145 offset:3072
	ds_read_b128 v[222:225], v145 offset:4096
	ds_read_b128 v[226:229], v145 offset:5120
	ds_read_b128 v[230:233], v145 offset:6144
	ds_read_b128 v[234:237], v145 offset:7168
	global_load_lds_dwordx4 v[162:163], off
	v_lshl_add_u64 v[162:163], s[18:19], 0, v[134:135]
	s_add_i32 m0, s43, 0xe000
	s_nop 0
	global_load_lds_dwordx4 v[162:163], off
	s_waitcnt vmcnt(8)
	s_waitcnt lgkmcnt(0)
	s_barrier
	v_mfma_f32_16x16x32_bf16 v[124:127], v[138:141], v[192:195], v[124:127]
	v_mfma_f32_16x16x32_bf16 v[116:119], v[150:153], v[192:195], v[116:119]
	v_mfma_f32_16x16x32_bf16 v[108:111], v[138:141], v[214:217], v[108:111]
	v_mfma_f32_16x16x32_bf16 v[100:103], v[150:153], v[214:217], v[100:103]
	v_mfma_f32_16x16x32_bf16 v[92:95], v[138:141], v[222:225], v[92:95]
	v_mfma_f32_16x16x32_bf16 v[84:87], v[150:153], v[222:225], v[84:87]
	v_mfma_f32_16x16x32_bf16 v[76:79], v[138:141], v[230:233], v[76:79]
	v_mfma_f32_16x16x32_bf16 v[68:71], v[150:153], v[230:233], v[68:71]
	v_mfma_f32_16x16x32_bf16 v[124:127], v[146:149], v[196:199], v[124:127]
	v_mfma_f32_16x16x32_bf16 v[116:119], v[154:157], v[196:199], v[116:119]
	v_mfma_f32_16x16x32_bf16 v[108:111], v[146:149], v[218:221], v[108:111]
	v_mfma_f32_16x16x32_bf16 v[100:103], v[154:157], v[218:221], v[100:103]
	v_mfma_f32_16x16x32_bf16 v[92:95], v[146:149], v[226:229], v[92:95]
	v_mfma_f32_16x16x32_bf16 v[84:87], v[154:157], v[226:229], v[84:87]
	v_mfma_f32_16x16x32_bf16 v[76:79], v[146:149], v[234:237], v[76:79]
	v_mfma_f32_16x16x32_bf16 v[68:71], v[154:157], v[234:237], v[68:71]
	v_mfma_f32_16x16x32_bf16 v[120:123], v[158:161], v[192:195], v[120:123]
	v_mfma_f32_16x16x32_bf16 v[112:115], v[184:187], v[192:195], v[112:115]
	v_mfma_f32_16x16x32_bf16 v[104:107], v[158:161], v[214:217], v[104:107]
	v_mfma_f32_16x16x32_bf16 v[96:99], v[184:187], v[214:217], v[96:99]
	v_mfma_f32_16x16x32_bf16 v[88:91], v[158:161], v[222:225], v[88:91]
	v_mfma_f32_16x16x32_bf16 v[80:83], v[184:187], v[222:225], v[80:83]
	v_mfma_f32_16x16x32_bf16 v[72:75], v[158:161], v[230:233], v[72:75]
	v_mfma_f32_16x16x32_bf16 v[64:67], v[184:187], v[230:233], v[64:67]
	v_mfma_f32_16x16x32_bf16 v[120:123], v[180:183], v[196:199], v[120:123]
	v_mfma_f32_16x16x32_bf16 v[112:115], v[188:191], v[196:199], v[112:115]
	v_mfma_f32_16x16x32_bf16 v[104:107], v[180:183], v[218:221], v[104:107]
	v_mfma_f32_16x16x32_bf16 v[96:99], v[188:191], v[218:221], v[96:99]
	v_mfma_f32_16x16x32_bf16 v[88:91], v[180:183], v[226:229], v[88:91]
	v_mfma_f32_16x16x32_bf16 v[80:83], v[188:191], v[226:229], v[80:83]
	v_mfma_f32_16x16x32_bf16 v[72:75], v[180:183], v[234:237], v[72:75]
	v_mfma_f32_16x16x32_bf16 v[64:67], v[188:191], v[234:237], v[64:67]
	s_barrier
; #define PG8_STAGE(bufoff, gbase, voff) do { _Pragma("unroll") for (int _i = 0; _i < 2; ++_i) \
;         __builtin_amdgcn_global_load_lds((const unsigned*)((const char*)(gbase) + (voff)[_i]), (PG8_LAS unsigned*)(lds + (bufoff) + ldsw + _i * 8192), 16, 0, 0); } while (0)
; #define PG8_LDA(dst, b, h) do { _Pragma("unroll") for (int m = 0; m < 4; ++m) _Pragma("unroll") for (int k = 0; k < 2; ++k) dst[m][k] = *(const PG8_LAS bf16x8*)(lds + PG8_SA(b, h) + aoff + m * 2048 + k * 1024); } while (0)
; #define PG8_LDB(dst, b, h) do { _Pragma("unroll") for (int n = 0; n < 2; ++n) _Pragma("unroll") for (int k = 0; k < 2; ++k) dst[n][k] = *(const PG8_LAS bf16x8*)(lds + PG8_SB(b, h) + boff + n * 2048 + k * 1024); } while (0)
; #define PG8_MMA(ai, bj, At, Bt) do { __builtin_amdgcn_s_setprio(1); _Pragma("unroll") for (int m = 0; m < 4; ++m) _Pragma("unroll") for (int n = 0; n < 2; ++n) _Pragma("unroll") for (int k = 0; k < 2; ++k) \
;         acc[ai][bj][m][n] = __builtin_amdgcn_mfma_f32_16x16x32_bf16(Bt[n][k], At[m][k], acc[ai][bj][m][n], 0, 0, 0); __builtin_amdgcn_s_setprio(0); } while (0)
; #define PG8_WAIT_V(n) asm volatile("s_waitcnt vmcnt(" #n ")" ::: "memory")
; #define PG8_WAIT_L(n) asm volatile("s_waitcnt lgkmcnt(" #n ")" ::: "memory")
; #define PG8_BAR __builtin_amdgcn_s_barrier()
; #define PG8_SCHED __builtin_amdgcn_sched_barrier(0)
; template <class Epi, class Sched, bool ALIGN_EPI = false, bool SP2 = false>
; __device__ __forceinline__ void gemm_phase(PG8_LAS unsigned char* lds, const Gemm g, const Sched& S, const Epi& E, const int tid) {
;     ...
;             PG8_LDA(At, 0, 1); PG8_STAGE(PG8_SB(0, 0), b2, voffB); PG8_STAGE(PG8_SB(0, 1), b2 + hstep, voffB); PG8_STAGE(PG8_SA(0, 0), a2, voffA);
;             PG8_WAIT_V(8); PG8_WAIT_L(0); PG8_BAR; PG8_MMA(1, 0, At, B0); PG8_MMA(1, 1, At, B1); PG8_BAR; PG8_SCHED;
;             PG8_LDB(B0, 1, 0); PG8_LDB(B1, 1, 1); PG8_SCHED; PG8_LDA(At, 1, 0); PG8_STAGE(PG8_SA(0, 1), a2 + hstep, voffA);
	s_add_i32 s60, s60, s41
	v_lshl_add_u64 v[162:163], s[20:21], 0, v[164:165]
	s_mov_b32 m0, s60
	ds_read_b128 v[192:195], v145 offset:16384
	ds_read_b128 v[196:199], v145 offset:17408
	ds_read_b128 v[214:217], v145 offset:18432
	ds_read_b128 v[218:221], v145 offset:19456
	ds_read_b128 v[222:225], v145 offset:20480
	ds_read_b128 v[226:229], v145 offset:21504
	ds_read_b128 v[230:233], v145 offset:22528
	ds_read_b128 v[234:237], v145 offset:23552
	global_load_lds_dwordx4 v[162:163], off
	s_add_i32 m0, s60, 0x2000
	s_add_u32 s60, s20, 0x40000
	v_lshl_add_u64 v[200:201], s[20:21], 0, v[128:129]
	s_addc_u32 s61, s21, 0
	s_add_i32 s62, s62, s41
	global_load_lds_dwordx4 v[200:201], off
	v_lshl_add_u64 v[238:239], s[60:61], 0, v[164:165]
	s_mov_b32 m0, s62
	v_lshl_add_u64 v[240:241], s[52:53], 0, v[130:131]
	global_load_lds_dwordx4 v[238:239], off
	v_lshl_add_u64 v[238:239], s[60:61], 0, v[128:129]
	s_add_i32 m0, s62, 0x2000
	s_nop 0
	global_load_lds_dwordx4 v[238:239], off
	v_lshl_add_u64 v[238:239], s[52:53], 0, v[132:133]
	s_mov_b32 m0, s43
	s_nop 0
	global_load_lds_dwordx4 v[238:239], off
	s_mov_b32 m0, s44
	s_nop 0
	global_load_lds_dwordx4 v[240:241], off
	s_waitcnt vmcnt(8)
	s_waitcnt lgkmcnt(0)
	s_barrier
	v_mfma_f32_16x16x32_bf16 v[60:63], v[138:141], v[192:195], v[60:63]
	v_mfma_f32_16x16x32_bf16 v[52:55], v[150:153], v[192:195], v[52:55]
	v_mfma_f32_16x16x32_bf16 v[44:47], v[138:141], v[214:217], v[44:47]
	v_mfma_f32_16x16x32_bf16 v[36:39], v[150:153], v[214:217], v[36:39]
	v_mfma_f32_16x16x32_bf16 v[28:31], v[138:141], v[222:225], v[28:31]
	v_mfma_f32_16x16x32_bf16 v[20:23], v[150:153], v[222:225], v[20:23]
	v_mfma_f32_16x16x32_bf16 v[12:15], v[138:141], v[230:233], v[12:15]
	v_mfma_f32_16x16x32_bf16 v[4:7], v[150:153], v[230:233], v[4:7]
	v_mfma_f32_16x16x32_bf16 v[60:63], v[146:149], v[196:199], v[60:63]
	v_mfma_f32_16x16x32_bf16 v[52:55], v[154:157], v[196:199], v[52:55]
	v_mfma_f32_16x16x32_bf16 v[44:47], v[146:149], v[218:221], v[44:47]
	v_mfma_f32_16x16x32_bf16 v[36:39], v[154:157], v[218:221], v[36:39]
	v_mfma_f32_16x16x32_bf16 v[28:31], v[146:149], v[226:229], v[28:31]
	v_mfma_f32_16x16x32_bf16 v[20:23], v[154:157], v[226:229], v[20:23]
	v_mfma_f32_16x16x32_bf16 v[12:15], v[146:149], v[234:237], v[12:15]
	v_mfma_f32_16x16x32_bf16 v[4:7], v[154:157], v[234:237], v[4:7]
	v_mfma_f32_16x16x32_bf16 v[56:59], v[158:161], v[192:195], v[56:59]
	v_mfma_f32_16x16x32_bf16 v[48:51], v[184:187], v[192:195], v[48:51]
	v_mfma_f32_16x16x32_bf16 v[40:43], v[158:161], v[214:217], v[40:43]
	v_mfma_f32_16x16x32_bf16 v[32:35], v[184:187], v[214:217], v[32:35]
	v_mfma_f32_16x16x32_bf16 v[24:27], v[158:161], v[222:225], v[24:27]
	v_mfma_f32_16x16x32_bf16 v[16:19], v[184:187], v[222:225], v[16:19]
	v_mfma_f32_16x16x32_bf16 v[8:11], v[158:161], v[230:233], v[8:11]
	v_mfma_f32_16x16x32_bf16 v[0:3], v[184:187], v[230:233], v[0:3]
	v_mfma_f32_16x16x32_bf16 v[56:59], v[180:183], v[196:199], v[56:59]
	v_mfma_f32_16x16x32_bf16 v[48:51], v[188:191], v[196:199], v[48:51]
	v_mfma_f32_16x16x32_bf16 v[40:43], v[180:183], v[218:221], v[40:43]
	v_mfma_f32_16x16x32_bf16 v[32:35], v[188:191], v[218:221], v[32:35]
	v_mfma_f32_16x16x32_bf16 v[24:27], v[180:183], v[226:229], v[24:27]
	v_mfma_f32_16x16x32_bf16 v[16:19], v[188:191], v[226:229], v[16:19]
	v_mfma_f32_16x16x32_bf16 v[8:11], v[180:183], v[234:237], v[8:11]
	v_mfma_f32_16x16x32_bf16 v[0:3], v[188:191], v[234:237], v[0:3]
	s_barrier
.Lsw_mid:
	s_add_i32 s60, 0, 0x18000
	s_add_i32 s61, 0, 0x1c000
	v_add_u32_e32 v154, s60, v143
	v_add_u32_e32 v166, s61, v143
	ds_read_b128 v[138:141], v154
	ds_read_b128 v[146:149], v154 offset:1024
	ds_read_b128 v[150:153], v154 offset:2048
	ds_read_b128 v[154:157], v154 offset:3072
	ds_read_b128 v[158:161], v166
	ds_read_b128 v[180:183], v166 offset:1024
	ds_read_b128 v[184:187], v166 offset:2048
	ds_read_b128 v[188:191], v166 offset:3072
	s_add_u32 s52, s52, 0x40000
	s_addc_u32 s53, s53, 0
	s_mov_b32 m0, s45
	v_lshl_add_u64 v[242:243], s[52:53], 0, v[132:133]
	ds_read_b128 v[192:195], v145 offset:32768
	ds_read_b128 v[196:199], v145 offset:33792
	ds_read_b128 v[214:217], v145 offset:34816
	ds_read_b128 v[218:221], v145 offset:35840
	ds_read_b128 v[222:225], v145 offset:36864
	ds_read_b128 v[226:229], v145 offset:37888
	ds_read_b128 v[230:233], v145 offset:38912
	ds_read_b128 v[234:237], v145 offset:39936
	global_load_lds_dwordx4 v[242:243], off
	v_lshl_add_u64 v[242:243], s[52:53], 0, v[130:131]
	s_mov_b32 m0, s48
	s_nop 0
	global_load_lds_dwordx4 v[242:243], off
	s_waitcnt vmcnt(8)
	s_waitcnt lgkmcnt(0)
	s_barrier
; #define PG8_STAGE(bufoff, gbase, voff) do { _Pragma("unroll") for (int _i = 0; _i < 2; ++_i) \
;         __builtin_amdgcn_global_load_lds((const unsigned*)((const char*)(gbase) + (voff)[_i]), (PG8_LAS unsigned*)(lds + (bufoff) + ldsw + _i * 8192), 16, 0, 0); } while (0)
; #define PG8_LDA(dst, b, h) do { _Pragma("unroll") for (int m = 0; m < 4; ++m) _Pragma("unroll") for (int k = 0; k < 2; ++k) dst[m][k] = *(const PG8_LAS bf16x8*)(lds + PG8_SA(b, h) + aoff + m * 2048 + k * 1024); } while (0)
; #define PG8_MMA(ai, bj, At, Bt) do { __builtin_amdgcn_s_setprio(1); _Pragma("unroll") for (int m = 0; m < 4; ++m) _Pragma("unroll") for (int n = 0; n < 2; ++n) _Pragma("unroll") for (int k = 0; k < 2; ++k) \
;         acc[ai][bj][m][n] = __builtin_amdgcn_mfma_f32_16x16x32_bf16(Bt[n][k], At[m][k], acc[ai][bj][m][n], 0, 0, 0); __builtin_amdgcn_s_setprio(0); } while (0)
; #define PG8_WAIT_V(n) asm volatile("s_waitcnt vmcnt(" #n ")" ::: "memory")
; #define PG8_WAIT_L(n) asm volatile("s_waitcnt lgkmcnt(" #n ")" ::: "memory")
; #define PG8_BAR __builtin_amdgcn_s_barrier()
; #define PG8_SCHED __builtin_amdgcn_sched_barrier(0)
; template <class Epi, class Sched, bool ALIGN_EPI = false, bool SP2 = false>
; __device__ __forceinline__ void gemm_phase(PG8_LAS unsigned char* lds, const Gemm g, const Sched& S, const Epi& E, const int tid) {
;     ...
;         for (int t = 0; t < nt; t += 2) {
;     ...
;             PG8_WAIT_V(8); PG8_WAIT_L(0); PG8_BAR; PG8_MMA(0, 0, At, B0); PG8_MMA(0, 1, At, B1); PG8_BAR; PG8_SCHED;
;             PG8_LDA(At, 1, 1); PG8_STAGE(PG8_SB(1, 0), b3, voffB); PG8_STAGE(PG8_SB(1, 1), b3 + hstep, voffB); PG8_STAGE(PG8_SA(1, 0), a3, voffA);
;             PG8_WAIT_V(8); PG8_WAIT_L(0); PG8_BAR; PG8_MMA(1, 0, At, B0); PG8_MMA(1, 1, At, B1); PG8_BAR; PG8_SCHED;
	v_mfma_f32_16x16x32_bf16 v[124:127], v[138:141], v[192:195], v[124:127]
	v_mfma_f32_16x16x32_bf16 v[116:119], v[150:153], v[192:195], v[116:119]
	v_mfma_f32_16x16x32_bf16 v[108:111], v[138:141], v[214:217], v[108:111]
	v_mfma_f32_16x16x32_bf16 v[100:103], v[150:153], v[214:217], v[100:103]
	v_mfma_f32_16x16x32_bf16 v[92:95], v[138:141], v[222:225], v[92:95]
	v_mfma_f32_16x16x32_bf16 v[84:87], v[150:153], v[222:225], v[84:87]
	v_mfma_f32_16x16x32_bf16 v[76:79], v[138:141], v[230:233], v[76:79]
	v_mfma_f32_16x16x32_bf16 v[68:71], v[150:153], v[230:233], v[68:71]
	v_mfma_f32_16x16x32_bf16 v[124:127], v[146:149], v[196:199], v[124:127]
	v_mfma_f32_16x16x32_bf16 v[116:119], v[154:157], v[196:199], v[116:119]
	v_mfma_f32_16x16x32_bf16 v[108:111], v[146:149], v[218:221], v[108:111]
	v_mfma_f32_16x16x32_bf16 v[100:103], v[154:157], v[218:221], v[100:103]
	v_mfma_f32_16x16x32_bf16 v[92:95], v[146:149], v[226:229], v[92:95]
	v_mfma_f32_16x16x32_bf16 v[84:87], v[154:157], v[226:229], v[84:87]
	v_mfma_f32_16x16x32_bf16 v[76:79], v[146:149], v[234:237], v[76:79]
	v_mfma_f32_16x16x32_bf16 v[68:71], v[154:157], v[234:237], v[68:71]
	v_mfma_f32_16x16x32_bf16 v[120:123], v[158:161], v[192:195], v[120:123]
	v_mfma_f32_16x16x32_bf16 v[112:115], v[184:187], v[192:195], v[112:115]
	v_mfma_f32_16x16x32_bf16 v[104:107], v[158:161], v[214:217], v[104:107]
	v_mfma_f32_16x16x32_bf16 v[96:99], v[184:187], v[214:217], v[96:99]
	v_mfma_f32_16x16x32_bf16 v[88:91], v[158:161], v[222:225], v[88:91]
	v_mfma_f32_16x16x32_bf16 v[80:83], v[184:187], v[222:225], v[80:83]
	v_mfma_f32_16x16x32_bf16 v[72:75], v[158:161], v[230:233], v[72:75]
	v_mfma_f32_16x16x32_bf16 v[64:67], v[184:187], v[230:233], v[64:67]
	v_mfma_f32_16x16x32_bf16 v[120:123], v[180:183], v[196:199], v[120:123]
	v_mfma_f32_16x16x32_bf16 v[112:115], v[188:191], v[196:199], v[112:115]
	v_mfma_f32_16x16x32_bf16 v[104:107], v[180:183], v[218:221], v[104:107]
	v_mfma_f32_16x16x32_bf16 v[96:99], v[188:191], v[218:221], v[96:99]
	v_mfma_f32_16x16x32_bf16 v[88:91], v[180:183], v[226:229], v[88:91]
	v_mfma_f32_16x16x32_bf16 v[80:83], v[188:191], v[226:229], v[80:83]
	v_mfma_f32_16x16x32_bf16 v[72:75], v[180:183], v[234:237], v[72:75]
	v_mfma_f32_16x16x32_bf16 v[64:67], v[188:191], v[234:237], v[64:67]
	s_barrier
	s_add_i32 s52, s60, s41
	v_lshl_add_u64 v[162:163], v[162:163], 0, s[86:87]
	s_mov_b32 m0, s52
	ds_read_b128 v[192:195], v145 offset:49152
	ds_read_b128 v[196:199], v145 offset:50176
	ds_read_b128 v[214:217], v145 offset:51200
	ds_read_b128 v[218:221], v145 offset:52224
	ds_read_b128 v[222:225], v145 offset:53248
	ds_read_b128 v[226:229], v145 offset:54272
	ds_read_b128 v[230:233], v145 offset:55296
	ds_read_b128 v[234:237], v145 offset:56320
	global_load_lds_dwordx4 v[162:163], off
	s_add_i32 m0, s52, 0x2000
	s_add_u32 s20, s20, 0x40080
	v_lshl_add_u64 v[162:163], v[200:201], 0, s[86:87]
	s_addc_u32 s21, s21, 0
	s_add_i32 s52, s61, s41
	global_load_lds_dwordx4 v[162:163], off
	v_lshl_add_u64 v[162:163], s[20:21], 0, v[164:165]
	s_mov_b32 m0, s52
	s_nop 0
	global_load_lds_dwordx4 v[162:163], off
	v_lshl_add_u64 v[162:163], s[20:21], 0, v[128:129]
	s_add_i32 m0, s52, 0x2000
	s_nop 0
	global_load_lds_dwordx4 v[162:163], off
	v_lshl_add_u64 v[162:163], v[238:239], 0, s[86:87]
	s_mov_b32 m0, s49
	s_nop 0
	global_load_lds_dwordx4 v[162:163], off
	v_lshl_add_u64 v[162:163], v[240:241], 0, s[86:87]
	s_mov_b32 m0, s50
	s_nop 0
	global_load_lds_dwordx4 v[162:163], off
	s_waitcnt vmcnt(8)
	s_waitcnt lgkmcnt(0)
	s_barrier
	v_mfma_f32_16x16x32_bf16 v[60:63], v[138:141], v[192:195], v[60:63]
	v_mfma_f32_16x16x32_bf16 v[52:55], v[150:153], v[192:195], v[52:55]
	v_mfma_f32_16x16x32_bf16 v[44:47], v[138:141], v[214:217], v[44:47]
	v_mfma_f32_16x16x32_bf16 v[36:39], v[150:153], v[214:217], v[36:39]
	v_mfma_f32_16x16x32_bf16 v[28:31], v[138:141], v[222:225], v[28:31]
	v_mfma_f32_16x16x32_bf16 v[20:23], v[150:153], v[222:225], v[20:23]
	v_mfma_f32_16x16x32_bf16 v[12:15], v[138:141], v[230:233], v[12:15]
	v_mfma_f32_16x16x32_bf16 v[4:7], v[150:153], v[230:233], v[4:7]
	v_mfma_f32_16x16x32_bf16 v[60:63], v[146:149], v[196:199], v[60:63]
	v_mfma_f32_16x16x32_bf16 v[52:55], v[154:157], v[196:199], v[52:55]
	v_mfma_f32_16x16x32_bf16 v[44:47], v[146:149], v[218:221], v[44:47]
	v_mfma_f32_16x16x32_bf16 v[36:39], v[154:157], v[218:221], v[36:39]
	v_mfma_f32_16x16x32_bf16 v[28:31], v[146:149], v[226:229], v[28:31]
	v_mfma_f32_16x16x32_bf16 v[20:23], v[154:157], v[226:229], v[20:23]
	v_mfma_f32_16x16x32_bf16 v[12:15], v[146:149], v[234:237], v[12:15]
	v_mfma_f32_16x16x32_bf16 v[4:7], v[154:157], v[234:237], v[4:7]
	v_mfma_f32_16x16x32_bf16 v[56:59], v[158:161], v[192:195], v[56:59]
	v_mfma_f32_16x16x32_bf16 v[48:51], v[184:187], v[192:195], v[48:51]
	v_mfma_f32_16x16x32_bf16 v[40:43], v[158:161], v[214:217], v[40:43]
	v_mfma_f32_16x16x32_bf16 v[32:35], v[184:187], v[214:217], v[32:35]
	v_mfma_f32_16x16x32_bf16 v[24:27], v[158:161], v[222:225], v[24:27]
	v_mfma_f32_16x16x32_bf16 v[16:19], v[184:187], v[222:225], v[16:19]
	v_mfma_f32_16x16x32_bf16 v[8:11], v[158:161], v[230:233], v[8:11]
	v_mfma_f32_16x16x32_bf16 v[0:3], v[184:187], v[230:233], v[0:3]
	v_mfma_f32_16x16x32_bf16 v[56:59], v[180:183], v[196:199], v[56:59]
	v_mfma_f32_16x16x32_bf16 v[48:51], v[188:191], v[196:199], v[48:51]
	v_mfma_f32_16x16x32_bf16 v[40:43], v[180:183], v[218:221], v[40:43]
	v_mfma_f32_16x16x32_bf16 v[32:35], v[188:191], v[218:221], v[32:35]
	v_mfma_f32_16x16x32_bf16 v[24:27], v[180:183], v[226:229], v[24:27]
	v_mfma_f32_16x16x32_bf16 v[16:19], v[188:191], v[226:229], v[16:19]
	v_mfma_f32_16x16x32_bf16 v[8:11], v[180:183], v[234:237], v[8:11]
	v_mfma_f32_16x16x32_bf16 v[0:3], v[188:191], v[234:237], v[0:3]
	s_barrier
	s_add_i32 s59, s59, 2
	s_add_u32 s57, s57, 0x100
	s_addc_u32 s58, s58, 0
	s_add_u32 s18, s18, 0x100
	s_addc_u32 s19, s19, 0
	s_cmp_gt_u32 s59, 13
	s_cbranch_scc0 .LBB0_1492
	s_and_b64 vcc, exec, s[6:7]
	s_cbranch_vccz .LBB0_1495
	s_barrier
